# comb21 + tile-boundary overlap in 12 of 19 GEMM instances (adds GEMM-P and the phase-A K/V^T GEMMs: their leading LDS wait moves with the reads)
# speedup vs baseline: 1.0085x; 1.0085x over previous
; #define PG8_STAGE(bufoff, gbase, voff) do { _Pragma("unroll") for (int _i = 0; _i < 2; ++_i) \
;         __builtin_amdgcn_global_load_lds((const unsigned*)((const char*)(gbase) + (voff)[_i]), (LAS unsigned*)(lds + (bufoff) + ldsw + _i * 8192), 16, 0, 0); } while (0)
; #define PG8_LDA(dst, b, h) do { _Pragma("unroll") for (int m = 0; m < 4; ++m) _Pragma("unroll") for (int k = 0; k < 2; ++k) dst[m][k] = *(const LAS bf16x8*)(lds + PG8_SA(b, h) + aoff + m * 2048 + k * 1024); } while (0)
; #define PG8_LDB(dst, b, h) do { _Pragma("unroll") for (int n = 0; n < 2; ++n) _Pragma("unroll") for (int k = 0; k < 2; ++k) dst[n][k] = *(const LAS bf16x8*)(lds + PG8_SB(b, h) + boff + n * 2048 + k * 1024); } while (0)
; #define PG8_SCHED __builtin_amdgcn_sched_barrier(0)
;     __device__ __forceinline__ bool next(int i, Unit& u) const {
;         const long L = (long)i * G + c; if (L >= nwg) return false;
;         int w = (int)L; { const int q = nwg / NXCD, r = nwg % NXCD, xcd = w % NXCD, off = w / NXCD; w = (xcd < r ? xcd * (q + 1) : r * (q + 1) + (xcd - r) * q) + off; }
;         u.pb = w / per; w -= u.pb * per;
;         const int nig = WGM * nN, gid = w / nig, fm = gid * WGM, gsz = (nM - fm) < WGM ? (nM - fm) : WGM;
;         u.pm = fm + ((w % nig) % gsz); u.pn = (w % nig) / gsz; return true;
;     }
; template <class Epi>
; __device__ __forceinline__ void gemm_phase(LAS unsigned char* lds, const Gemm g, int G, int c, const Epi& E) {
;     ...
;             PG8_LDB(B0, 0, 0); PG8_LDB(B1, 0, 1); PG8_SCHED; PG8_LDA(At, 0, 0); PG8_STAGE(PG8_SA(1, 1), a1 + hstepA, voffA);
.LBB0_231:
	s_waitcnt lgkmcnt(0)
	ds_read_b128 v[146:149], v152
	ds_read_b128 v[158:161], v152 offset:1024
	ds_read_b128 v[162:165], v152 offset:2048
	ds_read_b128 v[166:169], v152 offset:3072
	ds_read_b128 v[170:173], v153
	ds_read_b128 v[174:177], v153 offset:1024
	ds_read_b128 v[178:181], v153 offset:2048
	ds_read_b128 v[182:185], v153 offset:3072
	ds_read_b128 v[186:189], v154
	ds_read_b128 v[190:193], v154 offset:1024
	ds_read_b128 v[194:197], v154 offset:2048
	ds_read_b128 v[198:201], v154 offset:3072
	ds_read_b128 v[202:205], v154 offset:4096
	ds_read_b128 v[206:209], v154 offset:5120
	ds_read_b128 v[210:213], v154 offset:6144
	ds_read_b128 v[214:217], v154 offset:7168
	s_add_i32 s82, s82, 1
	s_mul_i32 s2, s82, s35
	s_mul_hi_u32 s3, s82, s27
	s_add_i32 s3, s3, s2
	s_mul_i32 s2, s82, s27
	s_add_u32 s2, s2, s26
	s_addc_u32 s3, s3, s34
	v_cmp_gt_i64_e32 vcc, s[2:3], v[144:145]
	v_cmp_lt_i64_e64 s[4:5], s[2:3], v[142:143]
	s_cbranch_vccnz .LBB0_233
	s_ashr_i32 s3, s2, 31
	s_lshr_b32 s3, s3, 29
	s_add_i32 s3, s2, s3
	s_ashr_i32 s7, s3, 3
	s_and_b32 s3, s3, -8
	s_sub_i32 s2, s2, s3
	s_cmp_lt_i32 s2, 0
	s_cselect_b32 s3, s78, 0x18c
	s_mul_i32 s2, s3, s2
	s_add_i32 s2, s2, s7
	s_mul_hi_i32 s3, s2, 0xa57eb503
	s_add_i32 s3, s3, s2
	s_lshr_b32 s7, s3, 31
	s_ashr_i32 s3, s3, 6
	s_add_i32 s83, s3, s7
	s_mul_i32 s3, s83, 0xffffff9d
	s_add_i32 s3, s3, s2
	s_mul_hi_i32 s2, s3, 0x2e8ba2e9
	s_lshr_b32 s7, s2, 31
	s_ashr_i32 s2, s2, 4
	s_add_i32 s2, s2, s7
	s_lshl_b32 s7, s2, 3
	s_sub_i32 s33, 9, s7
	s_min_i32 s33, s33, 8
	s_abs_i32 s42, s33
	v_cvt_f32_u32_e32 v2, s42
	s_sub_i32 s44, 0, s42
	s_mulk_i32 s2, 0x58
	s_sub_i32 s2, s3, s2
	v_rcp_iflag_f32_e32 v2, v2
	s_abs_i32 s3, s2
	s_xor_b32 s43, s2, s33
	s_ashr_i32 s43, s43, 31
	v_mul_f32_e32 v2, 0x4f7ffffe, v2
	v_cvt_u32_f32_e32 v2, v2
	s_nop 0
	v_readfirstlane_b32 s45, v2
	s_mul_i32 s44, s44, s45
	s_mul_hi_u32 s44, s45, s44
	s_add_i32 s45, s45, s44
	s_mul_hi_u32 s44, s3, s45
	s_mul_i32 s45, s44, s42
	s_sub_i32 s3, s3, s45
	s_add_i32 s45, s44, 1
	s_sub_i32 s46, s3, s42
	s_cmp_ge_u32 s3, s42
	s_cselect_b32 s44, s45, s44
	s_cselect_b32 s3, s46, s3
	s_add_i32 s45, s44, 1
	s_cmp_ge_u32 s3, s42
	s_cselect_b32 s3, s45, s44
	s_xor_b32 s3, s3, s43
	s_sub_i32 s42, s3, s43
	s_mul_i32 s3, s42, s33
	s_sub_i32 s2, s2, s3
	s_add_i32 s44, s2, s7

; #define PG8_STAGE(bufoff, gbase, voff) do { _Pragma("unroll") for (int _i = 0; _i < 2; ++_i) \
;         __builtin_amdgcn_global_load_lds((const unsigned*)((const char*)(gbase) + (voff)[_i]), (LAS unsigned*)(lds + (bufoff) + ldsw + _i * 8192), 16, 0, 0); } while (0)
; #define PG8_LDA(dst, b, h) do { _Pragma("unroll") for (int m = 0; m < 4; ++m) _Pragma("unroll") for (int k = 0; k < 2; ++k) dst[m][k] = *(const LAS bf16x8*)(lds + PG8_SA(b, h) + aoff + m * 2048 + k * 1024); } while (0)
; #define PG8_LDB(dst, b, h) do { _Pragma("unroll") for (int n = 0; n < 2; ++n) _Pragma("unroll") for (int k = 0; k < 2; ++k) dst[n][k] = *(const LAS bf16x8*)(lds + PG8_SB(b, h) + boff + n * 2048 + k * 1024); } while (0)
; #define PG8_MMA(ai, bj, At, Bt) do { __builtin_amdgcn_s_setprio(1); _Pragma("unroll") for (int m = 0; m < 4; ++m) _Pragma("unroll") for (int n = 0; n < 2; ++n) _Pragma("unroll") for (int k = 0; k < 2; ++k) \
;         acc[ai][bj][m][n] = __builtin_amdgcn_mfma_f32_16x16x32_bf16(Bt[n][k], At[m][k], acc[ai][bj][m][n], 0, 0, 0); __builtin_amdgcn_s_setprio(0); } while (0)
; #define PG8_BAR __builtin_amdgcn_s_barrier()
; template <class Epi>
; __device__ __forceinline__ void gemm_phase(LAS unsigned char* lds, const Gemm g, int G, int c, const Epi& E) {
;     ...
;         const char* nA = has_next ? (const char*)(g.A + (size_t)nxt.pb * g.sA) + (size_t)nxt.pm * 2 * hstepA : cA;
;         const char* nB = has_next ? (const char*)(g.Bt + (size_t)nxt.pb * g.sB) + (size_t)nxt.pn * 2 * hstepB : cB;
; #pragma nounroll
;         for (int t = 0; t < nt; t += 2) {
;             const bool last = (t == nt - 2);
;             const char* a1 = cA + (size_t)(t + 1) * kstep;
;             const char* a2 = last ? nA : cA + (size_t)(t + 2) * kstep; const char* b2 = last ? nB : cB + (size_t)(t + 2) * kstep;
;             const char* a3 = a2 + kstep; const char* b3 = b2 + kstep;
;             PG8_LDB(B0, 0, 0); PG8_LDB(B1, 0, 1); PG8_SCHED; PG8_LDA(At, 0, 0); PG8_STAGE(PG8_SA(1, 1), a1 + hstepA, voffA);
;             PG8_WAIT_V(8); PG8_WAIT_L(0); PG8_BAR; PG8_MMA(0, 0, At, B0); PG8_MMA(0, 1, At, B1); PG8_BAR; PG8_SCHED;
;             PG8_LDA(At, 0, 1); PG8_STAGE(PG8_SB(0, 0), b2, voffB); PG8_STAGE(PG8_SB(0, 1), b2 + hstepB, voffB); PG8_STAGE(PG8_SA(0, 0), a2, voffA);
;             PG8_WAIT_V(8); PG8_WAIT_L(0); PG8_BAR; PG8_MMA(1, 0, At, B0); PG8_MMA(1, 1, At, B1); PG8_BAR; PG8_SCHED;
.LBB0_235:
	s_ashr_i32 s43, s42, 31
	s_lshl_b64 s[52:53], s[42:43], 19
	s_add_u32 s52, s30, s52
	s_addc_u32 s53, s31, s53
	s_and_b64 s[4:5], s[4:5], exec
	s_cselect_b32 s7, s53, s55
	s_cselect_b32 s43, s52, s54
	s_add_u32 s4, s56, 0x40080
	s_addc_u32 s5, s57, 0
	s_add_u32 s45, s54, 0x100
	s_addc_u32 s84, s55, 0
	s_mov_b32 s85, -2
	s_add_u32 s33, s4, 0xfffc0080
	s_addc_u32 s54, s5, -1
	s_cmp_eq_u32 s85, 12
	s_cselect_b32 s57, s47, s54
	s_cselect_b32 s56, s46, s33
	s_cselect_b32 s55, s7, s84
	s_cselect_b32 s54, s43, s45
	v_lshl_add_u64 v[218:219], s[4:5], 0, v[138:139]
	s_add_i32 m0, s11, 0xc000
	global_load_lds_dwordx4 v[218:219], off
	v_lshl_add_u64 v[218:219], s[4:5], 0, v[140:141]
	s_add_i32 m0, s11, 0xe000
	s_nop 0
	global_load_lds_dwordx4 v[218:219], off
	s_waitcnt vmcnt(8)
	s_waitcnt lgkmcnt(0)
	s_barrier
	s_setprio 0
	v_mfma_f32_16x16x32_bf16 v[126:129], v[146:149], v[186:189], 0
	v_mfma_f32_16x16x32_bf16 v[122:125], v[162:165], v[186:189], 0
	v_mfma_f32_16x16x32_bf16 v[110:113], v[146:149], v[194:197], 0
	v_mfma_f32_16x16x32_bf16 v[106:109], v[162:165], v[194:197], 0
	v_mfma_f32_16x16x32_bf16 v[94:97], v[146:149], v[202:205], 0
	v_mfma_f32_16x16x32_bf16 v[90:93], v[162:165], v[202:205], 0
	v_mfma_f32_16x16x32_bf16 v[78:81], v[146:149], v[210:213], 0
	v_mfma_f32_16x16x32_bf16 v[74:77], v[162:165], v[210:213], 0
	v_mfma_f32_16x16x32_bf16 v[126:129], v[158:161], v[190:193], v[126:129]
	v_mfma_f32_16x16x32_bf16 v[122:125], v[166:169], v[190:193], v[122:125]
	v_mfma_f32_16x16x32_bf16 v[110:113], v[158:161], v[198:201], v[110:113]
	v_mfma_f32_16x16x32_bf16 v[106:109], v[166:169], v[198:201], v[106:109]
	v_mfma_f32_16x16x32_bf16 v[94:97], v[158:161], v[206:209], v[94:97]
	v_mfma_f32_16x16x32_bf16 v[90:93], v[166:169], v[206:209], v[90:93]
	v_mfma_f32_16x16x32_bf16 v[78:81], v[158:161], v[214:217], v[78:81]
	v_mfma_f32_16x16x32_bf16 v[74:77], v[166:169], v[214:217], v[74:77]
	s_setprio 2
	s_setprio 0
	v_mfma_f32_16x16x32_bf16 v[118:121], v[170:173], v[186:189], 0
	v_mfma_f32_16x16x32_bf16 v[114:117], v[178:181], v[186:189], 0
	v_mfma_f32_16x16x32_bf16 v[102:105], v[170:173], v[194:197], 0
	v_mfma_f32_16x16x32_bf16 v[98:101], v[178:181], v[194:197], 0
	v_mfma_f32_16x16x32_bf16 v[86:89], v[170:173], v[202:205], 0
	v_mfma_f32_16x16x32_bf16 v[82:85], v[178:181], v[202:205], 0
	v_mfma_f32_16x16x32_bf16 v[70:73], v[170:173], v[210:213], 0
	v_mfma_f32_16x16x32_bf16 v[66:69], v[178:181], v[210:213], 0
	v_mfma_f32_16x16x32_bf16 v[118:121], v[174:177], v[190:193], v[118:121]
	v_mfma_f32_16x16x32_bf16 v[114:117], v[182:185], v[190:193], v[114:117]
	v_mfma_f32_16x16x32_bf16 v[102:105], v[174:177], v[198:201], v[102:105]
	v_mfma_f32_16x16x32_bf16 v[98:101], v[182:185], v[198:201], v[98:101]
	v_mfma_f32_16x16x32_bf16 v[86:89], v[174:177], v[206:209], v[86:89]
	v_mfma_f32_16x16x32_bf16 v[82:85], v[182:185], v[206:209], v[82:85]
	v_mfma_f32_16x16x32_bf16 v[70:73], v[174:177], v[214:217], v[70:73]
	v_mfma_f32_16x16x32_bf16 v[66:69], v[182:185], v[214:217], v[66:69]
	s_setprio 2
	s_barrier
	s_add_i32 s33, s79, s60
	v_lshl_add_u64 v[218:219], s[54:55], 0, v[132:133]
	s_mov_b32 m0, s33
	ds_read_b128 v[186:189], v154 offset:16384
	ds_read_b128 v[190:193], v154 offset:17408
	ds_read_b128 v[194:197], v154 offset:18432
	ds_read_b128 v[198:201], v154 offset:19456
	ds_read_b128 v[202:205], v154 offset:20480
	ds_read_b128 v[206:209], v154 offset:21504
	ds_read_b128 v[210:213], v154 offset:22528
	ds_read_b128 v[214:217], v154 offset:23552
	global_load_lds_dwordx4 v[218:219], off
	s_add_i32 m0, s33, 0x2000
	s_add_u32 s62, s54, 0x40000
	v_lshl_add_u64 v[220:221], s[54:55], 0, v[136:137]
	s_addc_u32 s63, s55, 0
	s_add_i32 s33, s80, s60
	global_load_lds_dwordx4 v[220:221], off
	v_lshl_add_u64 v[222:223], s[62:63], 0, v[132:133]
	s_mov_b32 m0, s33
	v_lshl_add_u64 v[224:225], s[56:57], 0, v[134:135]
	global_load_lds_dwordx4 v[222:223], off
	v_lshl_add_u64 v[222:223], s[62:63], 0, v[136:137]
	s_add_i32 m0, s33, 0x2000
	s_nop 0
	global_load_lds_dwordx4 v[222:223], off
	v_lshl_add_u64 v[222:223], s[56:57], 0, v[130:131]
	s_mov_b32 m0, s11
	s_nop 0
	global_load_lds_dwordx4 v[222:223], off
	s_mov_b32 m0, s61
	s_nop 0
	global_load_lds_dwordx4 v[224:225], off
	s_waitcnt vmcnt(8)
	s_waitcnt lgkmcnt(0)
	s_barrier
	s_setprio 0
	v_mfma_f32_16x16x32_bf16 v[62:65], v[146:149], v[186:189], 0
	v_mfma_f32_16x16x32_bf16 v[58:61], v[162:165], v[186:189], 0
	v_mfma_f32_16x16x32_bf16 v[46:49], v[146:149], v[194:197], 0
	v_mfma_f32_16x16x32_bf16 v[42:45], v[162:165], v[194:197], 0
	v_mfma_f32_16x16x32_bf16 v[30:33], v[146:149], v[202:205], 0
	v_mfma_f32_16x16x32_bf16 v[26:29], v[162:165], v[202:205], 0
	v_mfma_f32_16x16x32_bf16 v[14:17], v[146:149], v[210:213], 0
	v_mfma_f32_16x16x32_bf16 v[10:13], v[162:165], v[210:213], 0
	v_mfma_f32_16x16x32_bf16 v[62:65], v[158:161], v[190:193], v[62:65]
	v_mfma_f32_16x16x32_bf16 v[58:61], v[166:169], v[190:193], v[58:61]
	v_mfma_f32_16x16x32_bf16 v[46:49], v[158:161], v[198:201], v[46:49]
	v_mfma_f32_16x16x32_bf16 v[42:45], v[166:169], v[198:201], v[42:45]
	v_mfma_f32_16x16x32_bf16 v[30:33], v[158:161], v[206:209], v[30:33]
	v_mfma_f32_16x16x32_bf16 v[26:29], v[166:169], v[206:209], v[26:29]
	v_mfma_f32_16x16x32_bf16 v[14:17], v[158:161], v[214:217], v[14:17]
	v_mfma_f32_16x16x32_bf16 v[10:13], v[166:169], v[214:217], v[10:13]
	s_setprio 2
	s_setprio 0
	v_mfma_f32_16x16x32_bf16 v[54:57], v[170:173], v[186:189], 0
	v_mfma_f32_16x16x32_bf16 v[50:53], v[178:181], v[186:189], 0
	v_mfma_f32_16x16x32_bf16 v[38:41], v[170:173], v[194:197], 0
	v_mfma_f32_16x16x32_bf16 v[34:37], v[178:181], v[194:197], 0
	v_mfma_f32_16x16x32_bf16 v[22:25], v[170:173], v[202:205], 0
	v_mfma_f32_16x16x32_bf16 v[18:21], v[178:181], v[202:205], 0
	v_mfma_f32_16x16x32_bf16 v[6:9], v[170:173], v[210:213], 0
	v_mfma_f32_16x16x32_bf16 v[2:5], v[178:181], v[210:213], 0
	v_mfma_f32_16x16x32_bf16 v[54:57], v[174:177], v[190:193], v[54:57]
	v_mfma_f32_16x16x32_bf16 v[50:53], v[182:185], v[190:193], v[50:53]
	v_mfma_f32_16x16x32_bf16 v[38:41], v[174:177], v[198:201], v[38:41]
	v_mfma_f32_16x16x32_bf16 v[34:37], v[182:185], v[198:201], v[34:37]
	v_mfma_f32_16x16x32_bf16 v[22:25], v[174:177], v[206:209], v[22:25]
	v_mfma_f32_16x16x32_bf16 v[18:21], v[182:185], v[206:209], v[18:21]
	v_mfma_f32_16x16x32_bf16 v[6:9], v[174:177], v[214:217], v[6:9]
	v_mfma_f32_16x16x32_bf16 v[2:5], v[182:185], v[214:217], v[2:5]
	s_setprio 2
	s_barrier
; #define PG8_STAGE(bufoff, gbase, voff) do { _Pragma("unroll") for (int _i = 0; _i < 2; ++_i) \
;         __builtin_amdgcn_global_load_lds((const unsigned*)((const char*)(gbase) + (voff)[_i]), (LAS unsigned*)(lds + (bufoff) + ldsw + _i * 8192), 16, 0, 0); } while (0)
; #define PG8_LDA(dst, b, h) do { _Pragma("unroll") for (int m = 0; m < 4; ++m) _Pragma("unroll") for (int k = 0; k < 2; ++k) dst[m][k] = *(const LAS bf16x8*)(lds + PG8_SA(b, h) + aoff + m * 2048 + k * 1024); } while (0)
; #define PG8_LDB(dst, b, h) do { _Pragma("unroll") for (int n = 0; n < 2; ++n) _Pragma("unroll") for (int k = 0; k < 2; ++k) dst[n][k] = *(const LAS bf16x8*)(lds + PG8_SB(b, h) + boff + n * 2048 + k * 1024); } while (0)
; #define PG8_MMA(ai, bj, At, Bt) do { __builtin_amdgcn_s_setprio(1); _Pragma("unroll") for (int m = 0; m < 4; ++m) _Pragma("unroll") for (int n = 0; n < 2; ++n) _Pragma("unroll") for (int k = 0; k < 2; ++k) \
;         acc[ai][bj][m][n] = __builtin_amdgcn_mfma_f32_16x16x32_bf16(Bt[n][k], At[m][k], acc[ai][bj][m][n], 0, 0, 0); __builtin_amdgcn_s_setprio(0); } while (0)
; #define PG8_WAIT_V(n) asm volatile("s_waitcnt vmcnt(" #n ")" ::: "memory")
; #define PG8_WAIT_L(n) asm volatile("s_waitcnt lgkmcnt(" #n ")" ::: "memory")
; #define PG8_BAR __builtin_amdgcn_s_barrier()
; #define PG8_SCHED __builtin_amdgcn_sched_barrier(0)
; template <class Epi>
; __device__ __forceinline__ void gemm_phase(LAS unsigned char* lds, const Gemm g, int G, int c, const Epi& E) {
;     ...
;             PG8_LDB(B0, 1, 0); PG8_LDB(B1, 1, 1); PG8_SCHED; PG8_LDA(At, 1, 0); PG8_STAGE(PG8_SA(0, 1), a2 + hstepA, voffA);
;             PG8_WAIT_V(8); PG8_WAIT_L(0); PG8_BAR; PG8_MMA(0, 0, At, B0); PG8_MMA(0, 1, At, B1); PG8_BAR; PG8_SCHED;
	s_add_i32 s33, 0, 0x18000
	v_add_u32_e32 v157, s33, v151
	s_add_i32 s62, 0, 0x1c000
	ds_read_b128 v[146:149], v157
	ds_read_b128 v[158:161], v157 offset:1024
	ds_read_b128 v[162:165], v157 offset:2048
	ds_read_b128 v[166:169], v157 offset:3072
	v_add_u32_e32 v157, s62, v151
	ds_read_b128 v[170:173], v157
	ds_read_b128 v[174:177], v157 offset:1024
	ds_read_b128 v[178:181], v157 offset:2048
	ds_read_b128 v[182:185], v157 offset:3072
	s_add_u32 s56, s56, 0x40000
	s_addc_u32 s57, s57, 0
	s_mov_b32 m0, s66
	v_lshl_add_u64 v[226:227], s[56:57], 0, v[130:131]
	ds_read_b128 v[186:189], v154 offset:32768
	ds_read_b128 v[190:193], v154 offset:33792
	ds_read_b128 v[194:197], v154 offset:34816
	ds_read_b128 v[198:201], v154 offset:35840
	ds_read_b128 v[202:205], v154 offset:36864
	ds_read_b128 v[206:209], v154 offset:37888
	ds_read_b128 v[210:213], v154 offset:38912
	ds_read_b128 v[214:217], v154 offset:39936
	global_load_lds_dwordx4 v[226:227], off
	v_lshl_add_u64 v[226:227], s[56:57], 0, v[134:135]
	s_mov_b32 m0, s67
	s_nop 0
	global_load_lds_dwordx4 v[226:227], off
	s_waitcnt vmcnt(8)
	s_waitcnt lgkmcnt(0)
	s_barrier
	s_setprio 0
	v_mfma_f32_16x16x32_bf16 v[126:129], v[146:149], v[186:189], v[126:129]
	v_mfma_f32_16x16x32_bf16 v[122:125], v[162:165], v[186:189], v[122:125]
	v_mfma_f32_16x16x32_bf16 v[110:113], v[146:149], v[194:197], v[110:113]
	v_mfma_f32_16x16x32_bf16 v[106:109], v[162:165], v[194:197], v[106:109]
	v_mfma_f32_16x16x32_bf16 v[94:97], v[146:149], v[202:205], v[94:97]
	v_mfma_f32_16x16x32_bf16 v[90:93], v[162:165], v[202:205], v[90:93]
	v_mfma_f32_16x16x32_bf16 v[78:81], v[146:149], v[210:213], v[78:81]
	v_mfma_f32_16x16x32_bf16 v[74:77], v[162:165], v[210:213], v[74:77]
	v_mfma_f32_16x16x32_bf16 v[126:129], v[158:161], v[190:193], v[126:129]
	v_mfma_f32_16x16x32_bf16 v[122:125], v[166:169], v[190:193], v[122:125]
	v_mfma_f32_16x16x32_bf16 v[110:113], v[158:161], v[198:201], v[110:113]
	v_mfma_f32_16x16x32_bf16 v[106:109], v[166:169], v[198:201], v[106:109]
	v_mfma_f32_16x16x32_bf16 v[94:97], v[158:161], v[206:209], v[94:97]
	v_mfma_f32_16x16x32_bf16 v[90:93], v[166:169], v[206:209], v[90:93]
	v_mfma_f32_16x16x32_bf16 v[78:81], v[158:161], v[214:217], v[78:81]
	v_mfma_f32_16x16x32_bf16 v[74:77], v[166:169], v[214:217], v[74:77]
	s_setprio 2
	s_setprio 0
	v_mfma_f32_16x16x32_bf16 v[118:121], v[170:173], v[186:189], v[118:121]
	v_mfma_f32_16x16x32_bf16 v[114:117], v[178:181], v[186:189], v[114:117]
	v_mfma_f32_16x16x32_bf16 v[102:105], v[170:173], v[194:197], v[102:105]
	v_mfma_f32_16x16x32_bf16 v[98:101], v[178:181], v[194:197], v[98:101]
	v_mfma_f32_16x16x32_bf16 v[86:89], v[170:173], v[202:205], v[86:89]
	v_mfma_f32_16x16x32_bf16 v[82:85], v[178:181], v[202:205], v[82:85]
	v_mfma_f32_16x16x32_bf16 v[70:73], v[170:173], v[210:213], v[70:73]
	v_mfma_f32_16x16x32_bf16 v[66:69], v[178:181], v[210:213], v[66:69]
	v_mfma_f32_16x16x32_bf16 v[118:121], v[174:177], v[190:193], v[118:121]
	v_mfma_f32_16x16x32_bf16 v[114:117], v[182:185], v[190:193], v[114:117]
	v_mfma_f32_16x16x32_bf16 v[102:105], v[174:177], v[198:201], v[102:105]
	v_mfma_f32_16x16x32_bf16 v[98:101], v[182:185], v[198:201], v[98:101]
	v_mfma_f32_16x16x32_bf16 v[86:89], v[174:177], v[206:209], v[86:89]
	v_mfma_f32_16x16x32_bf16 v[82:85], v[182:185], v[206:209], v[82:85]
	v_mfma_f32_16x16x32_bf16 v[70:73], v[174:177], v[214:217], v[70:73]
	v_mfma_f32_16x16x32_bf16 v[66:69], v[182:185], v[214:217], v[66:69]
	s_setprio 2
	s_barrier
; #define PG8_STAGE(bufoff, gbase, voff) do { _Pragma("unroll") for (int _i = 0; _i < 2; ++_i) \
;         __builtin_amdgcn_global_load_lds((const unsigned*)((const char*)(gbase) + (voff)[_i]), (LAS unsigned*)(lds + (bufoff) + ldsw + _i * 8192), 16, 0, 0); } while (0)
; #define PG8_LDA(dst, b, h) do { _Pragma("unroll") for (int m = 0; m < 4; ++m) _Pragma("unroll") for (int k = 0; k < 2; ++k) dst[m][k] = *(const LAS bf16x8*)(lds + PG8_SA(b, h) + aoff + m * 2048 + k * 1024); } while (0)
; #define PG8_MMA(ai, bj, At, Bt) do { __builtin_amdgcn_s_setprio(1); _Pragma("unroll") for (int m = 0; m < 4; ++m) _Pragma("unroll") for (int n = 0; n < 2; ++n) _Pragma("unroll") for (int k = 0; k < 2; ++k) \
;         acc[ai][bj][m][n] = __builtin_amdgcn_mfma_f32_16x16x32_bf16(Bt[n][k], At[m][k], acc[ai][bj][m][n], 0, 0, 0); __builtin_amdgcn_s_setprio(0); } while (0)
; #define PG8_WAIT_V(n) asm volatile("s_waitcnt vmcnt(" #n ")" ::: "memory")
; #define PG8_WAIT_L(n) asm volatile("s_waitcnt lgkmcnt(" #n ")" ::: "memory")
; #define PG8_BAR __builtin_amdgcn_s_barrier()
; #define PG8_SCHED __builtin_amdgcn_sched_barrier(0)
; template <class Epi>
; __device__ __forceinline__ void gemm_phase(LAS unsigned char* lds, const Gemm g, int G, int c, const Epi& E) {
;     ...
;             PG8_LDA(At, 1, 1); PG8_STAGE(PG8_SB(1, 0), b3, voffB); PG8_STAGE(PG8_SB(1, 1), b3 + hstepB, voffB); PG8_STAGE(PG8_SA(1, 0), a3, voffA);
;             PG8_WAIT_V(8); PG8_WAIT_L(0); PG8_BAR; PG8_MMA(1, 0, At, B0); PG8_MMA(1, 1, At, B1); PG8_BAR; PG8_SCHED;
;         }
	s_add_i32 s33, s33, s60
	v_lshl_add_u64 v[218:219], v[218:219], 0, s[20:21]
	s_mov_b32 m0, s33
	ds_read_b128 v[186:189], v154 offset:49152
	ds_read_b128 v[190:193], v154 offset:50176
	ds_read_b128 v[194:197], v154 offset:51200
	ds_read_b128 v[198:201], v154 offset:52224
	ds_read_b128 v[202:205], v154 offset:53248
	ds_read_b128 v[206:209], v154 offset:54272
	ds_read_b128 v[210:213], v154 offset:55296
	ds_read_b128 v[214:217], v154 offset:56320
	global_load_lds_dwordx4 v[218:219], off
	s_add_i32 m0, s33, 0x2000
	s_add_u32 s54, s54, 0x40080
	v_lshl_add_u64 v[218:219], v[220:221], 0, s[20:21]
	s_addc_u32 s55, s55, 0
	s_add_i32 s33, s62, s60
	global_load_lds_dwordx4 v[218:219], off
	v_lshl_add_u64 v[218:219], s[54:55], 0, v[132:133]
	s_mov_b32 m0, s33
	s_nop 0
	global_load_lds_dwordx4 v[218:219], off
	v_lshl_add_u64 v[218:219], s[54:55], 0, v[136:137]
	s_add_i32 m0, s33, 0x2000
	s_nop 0
	global_load_lds_dwordx4 v[218:219], off
	v_lshl_add_u64 v[218:219], v[222:223], 0, s[20:21]
	s_mov_b32 m0, s71
	s_nop 0
	global_load_lds_dwordx4 v[218:219], off
	v_lshl_add_u64 v[218:219], v[224:225], 0, s[20:21]
	s_mov_b32 m0, s72
	s_nop 0
	global_load_lds_dwordx4 v[218:219], off
	s_waitcnt vmcnt(8)
	s_waitcnt lgkmcnt(0)
	s_barrier
	s_setprio 0
	v_mfma_f32_16x16x32_bf16 v[62:65], v[146:149], v[186:189], v[62:65]
	v_mfma_f32_16x16x32_bf16 v[58:61], v[162:165], v[186:189], v[58:61]
	v_mfma_f32_16x16x32_bf16 v[46:49], v[146:149], v[194:197], v[46:49]
	v_mfma_f32_16x16x32_bf16 v[42:45], v[162:165], v[194:197], v[42:45]
	v_mfma_f32_16x16x32_bf16 v[30:33], v[146:149], v[202:205], v[30:33]
	v_mfma_f32_16x16x32_bf16 v[26:29], v[162:165], v[202:205], v[26:29]
	v_mfma_f32_16x16x32_bf16 v[14:17], v[146:149], v[210:213], v[14:17]
	v_mfma_f32_16x16x32_bf16 v[10:13], v[162:165], v[210:213], v[10:13]
	v_mfma_f32_16x16x32_bf16 v[62:65], v[158:161], v[190:193], v[62:65]
	v_mfma_f32_16x16x32_bf16 v[58:61], v[166:169], v[190:193], v[58:61]
	v_mfma_f32_16x16x32_bf16 v[46:49], v[158:161], v[198:201], v[46:49]
	v_mfma_f32_16x16x32_bf16 v[42:45], v[166:169], v[198:201], v[42:45]
	v_mfma_f32_16x16x32_bf16 v[30:33], v[158:161], v[206:209], v[30:33]
	v_mfma_f32_16x16x32_bf16 v[26:29], v[166:169], v[206:209], v[26:29]
	v_mfma_f32_16x16x32_bf16 v[14:17], v[158:161], v[214:217], v[14:17]
	v_mfma_f32_16x16x32_bf16 v[10:13], v[166:169], v[214:217], v[10:13]
	s_setprio 2
	s_setprio 0
	v_mfma_f32_16x16x32_bf16 v[54:57], v[170:173], v[186:189], v[54:57]
	v_mfma_f32_16x16x32_bf16 v[50:53], v[178:181], v[186:189], v[50:53]
	v_mfma_f32_16x16x32_bf16 v[38:41], v[170:173], v[194:197], v[38:41]
	v_mfma_f32_16x16x32_bf16 v[34:37], v[178:181], v[194:197], v[34:37]
	v_mfma_f32_16x16x32_bf16 v[22:25], v[170:173], v[202:205], v[22:25]
	v_mfma_f32_16x16x32_bf16 v[18:21], v[178:181], v[202:205], v[18:21]
	v_mfma_f32_16x16x32_bf16 v[6:9], v[170:173], v[210:213], v[6:9]
	v_mfma_f32_16x16x32_bf16 v[2:5], v[178:181], v[210:213], v[2:5]
	v_mfma_f32_16x16x32_bf16 v[54:57], v[174:177], v[190:193], v[54:57]
	v_mfma_f32_16x16x32_bf16 v[50:53], v[182:185], v[190:193], v[50:53]
	v_mfma_f32_16x16x32_bf16 v[38:41], v[174:177], v[198:201], v[38:41]
	v_mfma_f32_16x16x32_bf16 v[34:37], v[182:185], v[198:201], v[34:37]
	v_mfma_f32_16x16x32_bf16 v[22:25], v[174:177], v[206:209], v[22:25]
	v_mfma_f32_16x16x32_bf16 v[18:21], v[182:185], v[206:209], v[18:21]
	v_mfma_f32_16x16x32_bf16 v[6:9], v[174:177], v[214:217], v[6:9]
	v_mfma_f32_16x16x32_bf16 v[2:5], v[182:185], v[214:217], v[2:5]
	s_setprio 2
	s_barrier
	s_add_i32 s85, s85, 2
	s_add_u32 s4, s4, 0x100
	s_addc_u32 s5, s5, 0
	s_add_u32 s45, s45, 0x100
	s_addc_u32 s84, s84, 0
	s_cmp_gt_u32 s85, 13
	s_cbranch_scc0 .LBB0_236

; #define PG8_STAGE(bufoff, gbase, voff) do { _Pragma("unroll") for (int _i = 0; _i < 2; ++_i) \
;         __builtin_amdgcn_global_load_lds((const unsigned*)((const char*)(gbase) + (voff)[_i]), (LAS unsigned*)(lds + (bufoff) + ldsw + _i * 8192), 16, 0, 0); } while (0)
; #define PG8_LDA(dst, b, h) do { _Pragma("unroll") for (int m = 0; m < 4; ++m) _Pragma("unroll") for (int k = 0; k < 2; ++k) dst[m][k] = *(const LAS bf16x8*)(lds + PG8_SA(b, h) + aoff + m * 2048 + k * 1024); } while (0)
; #define PG8_LDB(dst, b, h) do { _Pragma("unroll") for (int n = 0; n < 2; ++n) _Pragma("unroll") for (int k = 0; k < 2; ++k) dst[n][k] = *(const LAS bf16x8*)(lds + PG8_SB(b, h) + boff + n * 2048 + k * 1024); } while (0)
; #define PG8_SCHED __builtin_amdgcn_sched_barrier(0)
;     __device__ __forceinline__ bool next(int i, Unit& u) const {
;         const long L = (long)i * G + c; if (L >= nwg) return false;
;         int w = (int)L; { const int q = nwg / NXCD, r = nwg % NXCD, xcd = w % NXCD, off = w / NXCD; w = (xcd < r ? xcd * (q + 1) : r * (q + 1) + (xcd - r) * q) + off; }
;         u.pb = w / per; w -= u.pb * per;
;         const int nig = WGM * nN, gid = w / nig, fm = gid * WGM, gsz = (nM - fm) < WGM ? (nM - fm) : WGM;
;         u.pm = fm + ((w % nig) % gsz); u.pn = (w % nig) / gsz; return true;
;     }
; template <class Epi>
; __device__ __forceinline__ void gemm_phase(LAS unsigned char* lds, const Gemm g, int G, int c, const Epi& E) {
;     ...
;             PG8_LDB(B0, 0, 0); PG8_LDB(B1, 0, 1); PG8_SCHED; PG8_LDA(At, 0, 0); PG8_STAGE(PG8_SA(1, 1), a1 + hstepA, voffA);
.LBB0_469:
	s_waitcnt lgkmcnt(0)
	ds_read_b128 v[130:133], v166
	ds_read_b128 v[134:137], v166 offset:1024
	ds_read_b128 v[150:153], v166 offset:2048
	ds_read_b128 v[154:157], v166 offset:3072
	ds_read_b128 v[158:161], v167
	ds_read_b128 v[172:175], v167 offset:1024
	ds_read_b128 v[176:179], v167 offset:2048
	ds_read_b128 v[180:183], v167 offset:3072
	ds_read_b128 v[184:187], v168
	ds_read_b128 v[188:191], v168 offset:1024
	ds_read_b128 v[192:195], v168 offset:2048
	ds_read_b128 v[196:199], v168 offset:3072
	ds_read_b128 v[200:203], v168 offset:4096
	ds_read_b128 v[204:207], v168 offset:5120
	ds_read_b128 v[208:211], v168 offset:6144
	ds_read_b128 v[212:215], v168 offset:7168
	s_add_i32 s90, s90, 1
	s_mul_i32 s2, s90, s70
	s_mul_hi_u32 s3, s90, s27
	s_add_i32 s3, s3, s2
	s_mul_i32 s2, s90, s27
	s_add_u32 s2, s2, s81
	s_addc_u32 s3, s3, s82
	v_cmp_gt_i64_e32 vcc, s[2:3], v[148:149]
	v_cmp_lt_i64_e64 s[4:5], s[2:3], v[146:147]
	s_cbranch_vccnz .LBB0_471
	s_ashr_i32 s3, s2, 31
	s_lshr_b32 s3, s3, 29
	s_add_i32 s3, s2, s3
	s_ashr_i32 s10, s3, 3
	s_and_b32 s3, s3, -8
	s_sub_i32 s2, s2, s3
	s_cmp_lt_i32 s2, 0
	s_movk_i32 s3, 0x6d
	s_cselect_b32 s3, s3, 0x6c
	s_mul_i32 s2, s3, s2
	s_add_i32 s2, s2, s10
	s_mul_hi_i32 s3, s2, 0x4bda12f7
	s_lshr_b32 s10, s3, 31
	s_ashr_i32 s3, s3, 3
	s_add_i32 s35, s3, s10
	s_mul_i32 s3, s35, 0xffffffe5
	s_add_i32 s3, s3, s2
	s_mul_hi_i32 s2, s3, 0x2aaaaaab
	s_lshr_b32 s10, s2, 31
	s_ashr_i32 s2, s2, 2
	s_add_i32 s2, s2, s10
	s_lshl_b32 s10, s2, 3
	s_sub_i32 s11, 9, s10
	s_min_i32 s11, s11, 8
	s_abs_i32 s14, s11
	v_cvt_f32_u32_e32 v2, s14
	s_sub_i32 s38, 0, s14
	s_mul_i32 s2, s2, 24
	s_sub_i32 s2, s3, s2
	v_rcp_iflag_f32_e32 v2, v2
	s_abs_i32 s3, s2
	s_xor_b32 s33, s2, s11
	s_ashr_i32 s33, s33, 31
	v_mul_f32_e32 v2, 0x4f7ffffe, v2
	v_cvt_u32_f32_e32 v2, v2
	s_nop 0
	v_readfirstlane_b32 s39, v2
	s_mul_i32 s38, s38, s39
	s_mul_hi_u32 s38, s39, s38
	s_add_i32 s39, s39, s38
	s_mul_hi_u32 s38, s3, s39
	s_mul_i32 s39, s38, s14
	s_sub_i32 s3, s3, s39
	s_add_i32 s39, s38, 1
	s_sub_i32 s46, s3, s14
	s_cmp_ge_u32 s3, s14
	s_cselect_b32 s38, s39, s38
	s_cselect_b32 s3, s46, s3
	s_add_i32 s39, s38, 1
	s_cmp_ge_u32 s3, s14
	s_cselect_b32 s3, s39, s38
	s_xor_b32 s3, s3, s33
	s_sub_i32 s72, s3, s33
	s_mul_i32 s3, s72, s11
	s_sub_i32 s2, s2, s3
	s_add_i32 s14, s2, s10

; #define PG8_STAGE(bufoff, gbase, voff) do { _Pragma("unroll") for (int _i = 0; _i < 2; ++_i) \
;         __builtin_amdgcn_global_load_lds((const unsigned*)((const char*)(gbase) + (voff)[_i]), (LAS unsigned*)(lds + (bufoff) + ldsw + _i * 8192), 16, 0, 0); } while (0)
; #define PG8_LDA(dst, b, h) do { _Pragma("unroll") for (int m = 0; m < 4; ++m) _Pragma("unroll") for (int k = 0; k < 2; ++k) dst[m][k] = *(const LAS bf16x8*)(lds + PG8_SA(b, h) + aoff + m * 2048 + k * 1024); } while (0)
; #define PG8_LDB(dst, b, h) do { _Pragma("unroll") for (int n = 0; n < 2; ++n) _Pragma("unroll") for (int k = 0; k < 2; ++k) dst[n][k] = *(const LAS bf16x8*)(lds + PG8_SB(b, h) + boff + n * 2048 + k * 1024); } while (0)
; #define PG8_MMA(ai, bj, At, Bt) do { __builtin_amdgcn_s_setprio(1); _Pragma("unroll") for (int m = 0; m < 4; ++m) _Pragma("unroll") for (int n = 0; n < 2; ++n) _Pragma("unroll") for (int k = 0; k < 2; ++k) \
;         acc[ai][bj][m][n] = __builtin_amdgcn_mfma_f32_16x16x32_bf16(Bt[n][k], At[m][k], acc[ai][bj][m][n], 0, 0, 0); __builtin_amdgcn_s_setprio(0); } while (0)
; #define PG8_WAIT_V(n) asm volatile("s_waitcnt vmcnt(" #n ")" ::: "memory")
; #define PG8_WAIT_L(n) asm volatile("s_waitcnt lgkmcnt(" #n ")" ::: "memory")
; #define PG8_BAR __builtin_amdgcn_s_barrier()
; #define PG8_SCHED __builtin_amdgcn_sched_barrier(0)
; template <class Epi>
; __device__ __forceinline__ void gemm_phase(LAS unsigned char* lds, const Gemm g, int G, int c, const Epi& E) {
;     ...
;             const bool last = (t == nt - 2);
;             const char* a1 = cA + (size_t)(t + 1) * kstep;
;             const char* a2 = last ? nA : cA + (size_t)(t + 2) * kstep; const char* b2 = last ? nB : cB + (size_t)(t + 2) * kstep;
;             const char* a3 = a2 + kstep; const char* b3 = b2 + kstep;
;             PG8_LDB(B0, 0, 0); PG8_LDB(B1, 0, 1); PG8_SCHED; PG8_LDA(At, 0, 0); PG8_STAGE(PG8_SA(1, 1), a1 + hstepA, voffA);
;             PG8_WAIT_V(8); PG8_WAIT_L(0); PG8_BAR; PG8_MMA(0, 0, At, B0); PG8_MMA(0, 1, At, B1); PG8_BAR; PG8_SCHED;
;             PG8_LDA(At, 0, 1); PG8_STAGE(PG8_SB(0, 0), b2, voffB); PG8_STAGE(PG8_SB(0, 1), b2 + hstepB, voffB); PG8_STAGE(PG8_SA(0, 0), a2, voffA);
;             PG8_WAIT_V(8); PG8_WAIT_L(0); PG8_BAR; PG8_MMA(1, 0, At, B0); PG8_MMA(1, 1, At, B1); PG8_BAR; PG8_SCHED;
.LBB0_475:
	s_mov_b32 s38, 0
	s_mov_b64 s[4:5], -1
	s_mov_b64 s[10:11], 0
	s_add_u32 s33, s8, s38
	s_addc_u32 s39, s9, 0
	s_add_u32 s56, s33, 0x100
	s_addc_u32 s57, s39, 0
	s_and_b64 s[54:55], s[10:11], exec
	s_cselect_b32 s57, s47, s57
	s_cselect_b32 s56, s46, s56
	s_add_u32 s38, s6, s38
	s_addc_u32 s54, s7, 0
	s_add_u32 s38, s38, 0x100
	s_addc_u32 s54, s54, 0
	s_and_b64 s[10:11], s[10:11], exec
	s_cselect_b32 s59, s53, s54
	s_cselect_b32 s58, s52, s38
	s_add_u32 s66, s33, 0xb0080
	s_addc_u32 s67, s39, 0
	s_add_i32 s63, s95, s83
	s_add_i32 m0, s86, 0xc000
	s_add_i32 s64, s86, 0xe000
	s_add_i32 s74, s63, 0x2000
	s_add_u32 s60, s58, 0xb0000
	s_addc_u32 s61, s59, 0
	s_add_i32 s75, s96, s83
	s_add_i32 s62, s75, 0x2000
	s_add_i32 vcc_hi, 0, 0x18000
	s_add_i32 vcc_lo, 0, 0x1c000
	s_add_u32 s54, s56, 0xb0000
	s_addc_u32 s55, s57, 0
	s_add_i32 s39, vcc_hi, s83
	s_add_i32 s73, s39, 0x2000
	s_add_u32 s10, s58, 0xb0080
	s_addc_u32 s11, s59, 0
	s_add_i32 s38, vcc_lo, s83
	s_add_i32 s33, s38, 0x2000
	v_lshl_add_u64 v[162:163], s[66:67], 0, v[138:139]
	global_load_lds_dwordx4 v[162:163], off
	v_lshl_add_u64 v[162:163], s[66:67], 0, v[142:143]
	s_mov_b32 m0, s64
	s_nop 0
	global_load_lds_dwordx4 v[162:163], off
	s_waitcnt vmcnt(8)
	s_waitcnt lgkmcnt(0)
	s_barrier
	s_setprio 0
	v_mfma_f32_16x16x32_bf16 v[126:129], v[130:133], v[184:187], 0
	v_mfma_f32_16x16x32_bf16 v[122:125], v[150:153], v[184:187], 0
	v_mfma_f32_16x16x32_bf16 v[110:113], v[130:133], v[192:195], 0
	v_mfma_f32_16x16x32_bf16 v[106:109], v[150:153], v[192:195], 0
	v_mfma_f32_16x16x32_bf16 v[94:97], v[130:133], v[200:203], 0
	v_mfma_f32_16x16x32_bf16 v[90:93], v[150:153], v[200:203], 0
	v_mfma_f32_16x16x32_bf16 v[78:81], v[130:133], v[208:211], 0
	v_mfma_f32_16x16x32_bf16 v[74:77], v[150:153], v[208:211], 0
	v_mfma_f32_16x16x32_bf16 v[126:129], v[134:137], v[188:191], v[126:129]
	v_mfma_f32_16x16x32_bf16 v[122:125], v[154:157], v[188:191], v[122:125]
	v_mfma_f32_16x16x32_bf16 v[110:113], v[134:137], v[196:199], v[110:113]
	v_mfma_f32_16x16x32_bf16 v[106:109], v[154:157], v[196:199], v[106:109]
	v_mfma_f32_16x16x32_bf16 v[94:97], v[134:137], v[204:207], v[94:97]
	v_mfma_f32_16x16x32_bf16 v[90:93], v[154:157], v[204:207], v[90:93]
	v_mfma_f32_16x16x32_bf16 v[78:81], v[134:137], v[212:215], v[78:81]
	v_mfma_f32_16x16x32_bf16 v[74:77], v[154:157], v[212:215], v[74:77]
	s_setprio 2
	s_setprio 0
	v_mfma_f32_16x16x32_bf16 v[118:121], v[158:161], v[184:187], 0
	v_mfma_f32_16x16x32_bf16 v[114:117], v[176:179], v[184:187], 0
	v_mfma_f32_16x16x32_bf16 v[102:105], v[158:161], v[192:195], 0
	v_mfma_f32_16x16x32_bf16 v[98:101], v[176:179], v[192:195], 0
	v_mfma_f32_16x16x32_bf16 v[86:89], v[158:161], v[200:203], 0
	v_mfma_f32_16x16x32_bf16 v[82:85], v[176:179], v[200:203], 0
	v_mfma_f32_16x16x32_bf16 v[70:73], v[158:161], v[208:211], 0
	v_mfma_f32_16x16x32_bf16 v[66:69], v[176:179], v[208:211], 0
	v_mfma_f32_16x16x32_bf16 v[118:121], v[172:175], v[188:191], v[118:121]
	v_mfma_f32_16x16x32_bf16 v[114:117], v[180:183], v[188:191], v[114:117]
	v_mfma_f32_16x16x32_bf16 v[102:105], v[172:175], v[196:199], v[102:105]
	v_mfma_f32_16x16x32_bf16 v[98:101], v[180:183], v[196:199], v[98:101]
	v_mfma_f32_16x16x32_bf16 v[86:89], v[172:175], v[204:207], v[86:89]
	v_mfma_f32_16x16x32_bf16 v[82:85], v[180:183], v[204:207], v[82:85]
	v_mfma_f32_16x16x32_bf16 v[70:73], v[172:175], v[212:215], v[70:73]
	v_mfma_f32_16x16x32_bf16 v[66:69], v[180:183], v[212:215], v[66:69]
	s_setprio 2
	s_barrier
	s_mov_b32 m0, s63
	v_lshl_add_u64 v[162:163], s[58:59], 0, v[140:141]
	ds_read_b128 v[184:187], v168 offset:16384
	ds_read_b128 v[188:191], v168 offset:17408
	ds_read_b128 v[192:195], v168 offset:18432
	ds_read_b128 v[196:199], v168 offset:19456
	ds_read_b128 v[200:203], v168 offset:20480
	ds_read_b128 v[204:207], v168 offset:21504
	ds_read_b128 v[208:211], v168 offset:22528
	ds_read_b128 v[212:215], v168 offset:23552
	global_load_lds_dwordx4 v[162:163], off
	v_lshl_add_u64 v[216:217], s[58:59], 0, v[144:145]
	s_mov_b32 m0, s74
	v_lshl_add_u64 v[218:219], s[60:61], 0, v[140:141]
	global_load_lds_dwordx4 v[216:217], off
	s_mov_b32 m0, s75
	v_lshl_add_u64 v[220:221], s[56:57], 0, v[142:143]
	global_load_lds_dwordx4 v[218:219], off
	v_lshl_add_u64 v[218:219], s[60:61], 0, v[144:145]
	s_mov_b32 m0, s62
	s_nop 0
	global_load_lds_dwordx4 v[218:219], off
	v_lshl_add_u64 v[218:219], s[56:57], 0, v[138:139]
	s_mov_b32 m0, s86
	s_nop 0
	global_load_lds_dwordx4 v[218:219], off
	s_mov_b32 m0, s87
	s_nop 0
	global_load_lds_dwordx4 v[220:221], off
	s_waitcnt vmcnt(8)
	s_waitcnt lgkmcnt(0)
	s_barrier
; #define PG8_STAGE(bufoff, gbase, voff) do { _Pragma("unroll") for (int _i = 0; _i < 2; ++_i) \
;         __builtin_amdgcn_global_load_lds((const unsigned*)((const char*)(gbase) + (voff)[_i]), (LAS unsigned*)(lds + (bufoff) + ldsw + _i * 8192), 16, 0, 0); } while (0)
; #define PG8_LDA(dst, b, h) do { _Pragma("unroll") for (int m = 0; m < 4; ++m) _Pragma("unroll") for (int k = 0; k < 2; ++k) dst[m][k] = *(const LAS bf16x8*)(lds + PG8_SA(b, h) + aoff + m * 2048 + k * 1024); } while (0)
; #define PG8_LDB(dst, b, h) do { _Pragma("unroll") for (int n = 0; n < 2; ++n) _Pragma("unroll") for (int k = 0; k < 2; ++k) dst[n][k] = *(const LAS bf16x8*)(lds + PG8_SB(b, h) + boff + n * 2048 + k * 1024); } while (0)
; #define PG8_MMA(ai, bj, At, Bt) do { __builtin_amdgcn_s_setprio(1); _Pragma("unroll") for (int m = 0; m < 4; ++m) _Pragma("unroll") for (int n = 0; n < 2; ++n) _Pragma("unroll") for (int k = 0; k < 2; ++k) \
;         acc[ai][bj][m][n] = __builtin_amdgcn_mfma_f32_16x16x32_bf16(Bt[n][k], At[m][k], acc[ai][bj][m][n], 0, 0, 0); __builtin_amdgcn_s_setprio(0); } while (0)
; #define PG8_WAIT_V(n) asm volatile("s_waitcnt vmcnt(" #n ")" ::: "memory")
; #define PG8_WAIT_L(n) asm volatile("s_waitcnt lgkmcnt(" #n ")" ::: "memory")
; #define PG8_BAR __builtin_amdgcn_s_barrier()
; #define PG8_SCHED __builtin_amdgcn_sched_barrier(0)
; template <class Epi>
; __device__ __forceinline__ void gemm_phase(LAS unsigned char* lds, const Gemm g, int G, int c, const Epi& E) {
;     ...
;             PG8_WAIT_V(8); PG8_WAIT_L(0); PG8_BAR; PG8_MMA(1, 0, At, B0); PG8_MMA(1, 1, At, B1); PG8_BAR; PG8_SCHED;
;             PG8_LDB(B0, 1, 0); PG8_LDB(B1, 1, 1); PG8_SCHED; PG8_LDA(At, 1, 0); PG8_STAGE(PG8_SA(0, 1), a2 + hstepA, voffA);
;             PG8_WAIT_V(8); PG8_WAIT_L(0); PG8_BAR; PG8_MMA(0, 0, At, B0); PG8_MMA(0, 1, At, B1); PG8_BAR; PG8_SCHED;
	s_setprio 0
	v_mfma_f32_16x16x32_bf16 v[62:65], v[130:133], v[184:187], 0
	v_mfma_f32_16x16x32_bf16 v[58:61], v[150:153], v[184:187], 0
	v_mfma_f32_16x16x32_bf16 v[46:49], v[130:133], v[192:195], 0
	v_mfma_f32_16x16x32_bf16 v[42:45], v[150:153], v[192:195], 0
	v_mfma_f32_16x16x32_bf16 v[30:33], v[130:133], v[200:203], 0
	v_mfma_f32_16x16x32_bf16 v[26:29], v[150:153], v[200:203], 0
	v_mfma_f32_16x16x32_bf16 v[14:17], v[130:133], v[208:211], 0
	v_mfma_f32_16x16x32_bf16 v[10:13], v[150:153], v[208:211], 0
	v_mfma_f32_16x16x32_bf16 v[62:65], v[134:137], v[188:191], v[62:65]
	v_mfma_f32_16x16x32_bf16 v[58:61], v[154:157], v[188:191], v[58:61]
	v_mfma_f32_16x16x32_bf16 v[46:49], v[134:137], v[196:199], v[46:49]
	v_mfma_f32_16x16x32_bf16 v[42:45], v[154:157], v[196:199], v[42:45]
	v_mfma_f32_16x16x32_bf16 v[30:33], v[134:137], v[204:207], v[30:33]
	v_mfma_f32_16x16x32_bf16 v[26:29], v[154:157], v[204:207], v[26:29]
	v_mfma_f32_16x16x32_bf16 v[14:17], v[134:137], v[212:215], v[14:17]
	v_mfma_f32_16x16x32_bf16 v[10:13], v[154:157], v[212:215], v[10:13]
	s_setprio 2
	s_setprio 0
	v_mfma_f32_16x16x32_bf16 v[54:57], v[158:161], v[184:187], 0
	v_mfma_f32_16x16x32_bf16 v[50:53], v[176:179], v[184:187], 0
	v_mfma_f32_16x16x32_bf16 v[38:41], v[158:161], v[192:195], 0
	v_mfma_f32_16x16x32_bf16 v[34:37], v[176:179], v[192:195], 0
	v_mfma_f32_16x16x32_bf16 v[22:25], v[158:161], v[200:203], 0
	v_mfma_f32_16x16x32_bf16 v[18:21], v[176:179], v[200:203], 0
	v_mfma_f32_16x16x32_bf16 v[6:9], v[158:161], v[208:211], 0
	v_mfma_f32_16x16x32_bf16 v[2:5], v[176:179], v[208:211], 0
	v_mfma_f32_16x16x32_bf16 v[54:57], v[172:175], v[188:191], v[54:57]
	v_mfma_f32_16x16x32_bf16 v[50:53], v[180:183], v[188:191], v[50:53]
	v_mfma_f32_16x16x32_bf16 v[38:41], v[172:175], v[196:199], v[38:41]
	v_mfma_f32_16x16x32_bf16 v[34:37], v[180:183], v[196:199], v[34:37]
	v_mfma_f32_16x16x32_bf16 v[22:25], v[172:175], v[204:207], v[22:25]
	v_mfma_f32_16x16x32_bf16 v[18:21], v[180:183], v[204:207], v[18:21]
	v_mfma_f32_16x16x32_bf16 v[6:9], v[172:175], v[212:215], v[6:9]
	v_mfma_f32_16x16x32_bf16 v[2:5], v[180:183], v[212:215], v[2:5]
	s_setprio 2
	s_barrier
	v_add_u32_e32 v154, vcc_hi, v165
	v_add_u32_e32 v180, vcc_lo, v165
	ds_read_b128 v[130:133], v154
	ds_read_b128 v[134:137], v154 offset:1024
	ds_read_b128 v[150:153], v154 offset:2048
	ds_read_b128 v[154:157], v154 offset:3072
	ds_read_b128 v[158:161], v180
	ds_read_b128 v[172:175], v180 offset:1024
	ds_read_b128 v[176:179], v180 offset:2048
	ds_read_b128 v[180:183], v180 offset:3072
	s_mov_b32 m0, s88
	v_lshl_add_u64 v[222:223], s[54:55], 0, v[138:139]
	ds_read_b128 v[184:187], v168 offset:32768
	ds_read_b128 v[188:191], v168 offset:33792
	ds_read_b128 v[192:195], v168 offset:34816
	ds_read_b128 v[196:199], v168 offset:35840
	ds_read_b128 v[200:203], v168 offset:36864
	ds_read_b128 v[204:207], v168 offset:37888
	ds_read_b128 v[208:211], v168 offset:38912
	ds_read_b128 v[212:215], v168 offset:39936
	global_load_lds_dwordx4 v[222:223], off
	v_lshl_add_u64 v[222:223], s[54:55], 0, v[142:143]
	s_mov_b32 m0, s89
	s_nop 0
	global_load_lds_dwordx4 v[222:223], off
	s_waitcnt vmcnt(8)
	s_waitcnt lgkmcnt(0)
	s_barrier
	s_setprio 0
	v_mfma_f32_16x16x32_bf16 v[126:129], v[130:133], v[184:187], v[126:129]
	v_mfma_f32_16x16x32_bf16 v[122:125], v[150:153], v[184:187], v[122:125]
	v_mfma_f32_16x16x32_bf16 v[110:113], v[130:133], v[192:195], v[110:113]
	v_mfma_f32_16x16x32_bf16 v[106:109], v[150:153], v[192:195], v[106:109]
	v_mfma_f32_16x16x32_bf16 v[94:97], v[130:133], v[200:203], v[94:97]
	v_mfma_f32_16x16x32_bf16 v[90:93], v[150:153], v[200:203], v[90:93]
	v_mfma_f32_16x16x32_bf16 v[78:81], v[130:133], v[208:211], v[78:81]
	v_mfma_f32_16x16x32_bf16 v[74:77], v[150:153], v[208:211], v[74:77]
	v_mfma_f32_16x16x32_bf16 v[126:129], v[134:137], v[188:191], v[126:129]
	v_mfma_f32_16x16x32_bf16 v[122:125], v[154:157], v[188:191], v[122:125]
	v_mfma_f32_16x16x32_bf16 v[110:113], v[134:137], v[196:199], v[110:113]
	v_mfma_f32_16x16x32_bf16 v[106:109], v[154:157], v[196:199], v[106:109]
	v_mfma_f32_16x16x32_bf16 v[94:97], v[134:137], v[204:207], v[94:97]
	v_mfma_f32_16x16x32_bf16 v[90:93], v[154:157], v[204:207], v[90:93]
	v_mfma_f32_16x16x32_bf16 v[78:81], v[134:137], v[212:215], v[78:81]
	v_mfma_f32_16x16x32_bf16 v[74:77], v[154:157], v[212:215], v[74:77]
	s_setprio 2
	s_setprio 0
	v_mfma_f32_16x16x32_bf16 v[118:121], v[158:161], v[184:187], v[118:121]
	v_mfma_f32_16x16x32_bf16 v[114:117], v[176:179], v[184:187], v[114:117]
	v_mfma_f32_16x16x32_bf16 v[102:105], v[158:161], v[192:195], v[102:105]
	v_mfma_f32_16x16x32_bf16 v[98:101], v[176:179], v[192:195], v[98:101]
	v_mfma_f32_16x16x32_bf16 v[86:89], v[158:161], v[200:203], v[86:89]
	v_mfma_f32_16x16x32_bf16 v[82:85], v[176:179], v[200:203], v[82:85]
	v_mfma_f32_16x16x32_bf16 v[70:73], v[158:161], v[208:211], v[70:73]
	v_mfma_f32_16x16x32_bf16 v[66:69], v[176:179], v[208:211], v[66:69]
	v_mfma_f32_16x16x32_bf16 v[118:121], v[172:175], v[188:191], v[118:121]
	v_mfma_f32_16x16x32_bf16 v[114:117], v[180:183], v[188:191], v[114:117]
	v_mfma_f32_16x16x32_bf16 v[102:105], v[172:175], v[196:199], v[102:105]
	v_mfma_f32_16x16x32_bf16 v[98:101], v[180:183], v[196:199], v[98:101]
	v_mfma_f32_16x16x32_bf16 v[86:89], v[172:175], v[204:207], v[86:89]
	v_mfma_f32_16x16x32_bf16 v[82:85], v[180:183], v[204:207], v[82:85]
	v_mfma_f32_16x16x32_bf16 v[70:73], v[172:175], v[212:215], v[70:73]
	v_mfma_f32_16x16x32_bf16 v[66:69], v[180:183], v[212:215], v[66:69]
	s_setprio 2
	s_barrier
; #define PG8_STAGE(bufoff, gbase, voff) do { _Pragma("unroll") for (int _i = 0; _i < 2; ++_i) \
;         __builtin_amdgcn_global_load_lds((const unsigned*)((const char*)(gbase) + (voff)[_i]), (LAS unsigned*)(lds + (bufoff) + ldsw + _i * 8192), 16, 0, 0); } while (0)
; #define PG8_LDA(dst, b, h) do { _Pragma("unroll") for (int m = 0; m < 4; ++m) _Pragma("unroll") for (int k = 0; k < 2; ++k) dst[m][k] = *(const LAS bf16x8*)(lds + PG8_SA(b, h) + aoff + m * 2048 + k * 1024); } while (0)
; #define PG8_MMA(ai, bj, At, Bt) do { __builtin_amdgcn_s_setprio(1); _Pragma("unroll") for (int m = 0; m < 4; ++m) _Pragma("unroll") for (int n = 0; n < 2; ++n) _Pragma("unroll") for (int k = 0; k < 2; ++k) \
;         acc[ai][bj][m][n] = __builtin_amdgcn_mfma_f32_16x16x32_bf16(Bt[n][k], At[m][k], acc[ai][bj][m][n], 0, 0, 0); __builtin_amdgcn_s_setprio(0); } while (0)
; #define PG8_WAIT_V(n) asm volatile("s_waitcnt vmcnt(" #n ")" ::: "memory")
; #define PG8_WAIT_L(n) asm volatile("s_waitcnt lgkmcnt(" #n ")" ::: "memory")
; #define PG8_BAR __builtin_amdgcn_s_barrier()
; #define PG8_SCHED __builtin_amdgcn_sched_barrier(0)
; template <class Epi>
; __device__ __forceinline__ void gemm_phase(LAS unsigned char* lds, const Gemm g, int G, int c, const Epi& E) {
;     ...
;             PG8_LDA(At, 1, 1); PG8_STAGE(PG8_SB(1, 0), b3, voffB); PG8_STAGE(PG8_SB(1, 1), b3 + hstepB, voffB); PG8_STAGE(PG8_SA(1, 0), a3, voffA);
;             PG8_WAIT_V(8); PG8_WAIT_L(0); PG8_BAR; PG8_MMA(1, 0, At, B0); PG8_MMA(1, 1, At, B1); PG8_BAR; PG8_SCHED;
;         }
	s_mov_b32 m0, s39
	v_lshl_add_u64 v[162:163], v[162:163], 0, s[24:25]
	ds_read_b128 v[184:187], v168 offset:49152
	ds_read_b128 v[188:191], v168 offset:50176
	ds_read_b128 v[192:195], v168 offset:51200
	ds_read_b128 v[196:199], v168 offset:52224
	ds_read_b128 v[200:203], v168 offset:53248
	ds_read_b128 v[204:207], v168 offset:54272
	ds_read_b128 v[208:211], v168 offset:55296
	ds_read_b128 v[212:215], v168 offset:56320
	global_load_lds_dwordx4 v[162:163], off
	v_lshl_add_u64 v[162:163], v[216:217], 0, s[24:25]
	s_mov_b32 m0, s73
	s_nop 0
	global_load_lds_dwordx4 v[162:163], off
	v_lshl_add_u64 v[162:163], s[10:11], 0, v[140:141]
	s_mov_b32 m0, s38
	s_nop 0
	global_load_lds_dwordx4 v[162:163], off
	v_lshl_add_u64 v[162:163], s[10:11], 0, v[144:145]
	s_mov_b32 m0, s33
	s_nop 0
	global_load_lds_dwordx4 v[162:163], off
	v_lshl_add_u64 v[162:163], v[218:219], 0, s[24:25]
	s_mov_b32 m0, s93
	s_nop 0
	global_load_lds_dwordx4 v[162:163], off
	v_lshl_add_u64 v[162:163], v[220:221], 0, s[24:25]
	s_mov_b32 m0, s94
	s_nop 0
	global_load_lds_dwordx4 v[162:163], off
	s_waitcnt vmcnt(8)
	s_waitcnt lgkmcnt(0)
	s_barrier
	s_setprio 0
	v_mfma_f32_16x16x32_bf16 v[62:65], v[130:133], v[184:187], v[62:65]
	v_mfma_f32_16x16x32_bf16 v[58:61], v[150:153], v[184:187], v[58:61]
	v_mfma_f32_16x16x32_bf16 v[46:49], v[130:133], v[192:195], v[46:49]
	v_mfma_f32_16x16x32_bf16 v[42:45], v[150:153], v[192:195], v[42:45]
	v_mfma_f32_16x16x32_bf16 v[30:33], v[130:133], v[200:203], v[30:33]
	v_mfma_f32_16x16x32_bf16 v[26:29], v[150:153], v[200:203], v[26:29]
	v_mfma_f32_16x16x32_bf16 v[14:17], v[130:133], v[208:211], v[14:17]
	v_mfma_f32_16x16x32_bf16 v[10:13], v[150:153], v[208:211], v[10:13]
	v_mfma_f32_16x16x32_bf16 v[62:65], v[134:137], v[188:191], v[62:65]
	v_mfma_f32_16x16x32_bf16 v[58:61], v[154:157], v[188:191], v[58:61]
	v_mfma_f32_16x16x32_bf16 v[46:49], v[134:137], v[196:199], v[46:49]
	v_mfma_f32_16x16x32_bf16 v[42:45], v[154:157], v[196:199], v[42:45]
	v_mfma_f32_16x16x32_bf16 v[30:33], v[134:137], v[204:207], v[30:33]
	v_mfma_f32_16x16x32_bf16 v[26:29], v[154:157], v[204:207], v[26:29]
	v_mfma_f32_16x16x32_bf16 v[14:17], v[134:137], v[212:215], v[14:17]
	v_mfma_f32_16x16x32_bf16 v[10:13], v[154:157], v[212:215], v[10:13]
	s_setprio 2
	s_setprio 0
	v_mfma_f32_16x16x32_bf16 v[54:57], v[158:161], v[184:187], v[54:57]
	v_mfma_f32_16x16x32_bf16 v[50:53], v[176:179], v[184:187], v[50:53]
	v_mfma_f32_16x16x32_bf16 v[38:41], v[158:161], v[192:195], v[38:41]
	v_mfma_f32_16x16x32_bf16 v[34:37], v[176:179], v[192:195], v[34:37]
	v_mfma_f32_16x16x32_bf16 v[22:25], v[158:161], v[200:203], v[22:25]
	v_mfma_f32_16x16x32_bf16 v[18:21], v[176:179], v[200:203], v[18:21]
	v_mfma_f32_16x16x32_bf16 v[6:9], v[158:161], v[208:211], v[6:9]
	v_mfma_f32_16x16x32_bf16 v[2:5], v[176:179], v[208:211], v[2:5]
	v_mfma_f32_16x16x32_bf16 v[54:57], v[172:175], v[188:191], v[54:57]
	v_mfma_f32_16x16x32_bf16 v[50:53], v[180:183], v[188:191], v[50:53]
	v_mfma_f32_16x16x32_bf16 v[38:41], v[172:175], v[196:199], v[38:41]
	v_mfma_f32_16x16x32_bf16 v[34:37], v[180:183], v[196:199], v[34:37]
	v_mfma_f32_16x16x32_bf16 v[22:25], v[172:175], v[204:207], v[22:25]
	v_mfma_f32_16x16x32_bf16 v[18:21], v[180:183], v[204:207], v[18:21]
	v_mfma_f32_16x16x32_bf16 v[6:9], v[172:175], v[212:215], v[6:9]
	v_mfma_f32_16x16x32_bf16 v[2:5], v[180:183], v[212:215], v[2:5]
	s_setprio 2
	s_barrier
	s_movk_i32 s38, 0x100
	s_andn2_b64 vcc, exec, s[4:5]
	s_mov_b64 s[10:11], -1
	s_mov_b64 s[4:5], 0
	s_cbranch_vccz .LBB0_476

; #define PG8_STAGE(bufoff, gbase, voff) do { _Pragma("unroll") for (int _i = 0; _i < 2; ++_i) \
;         __builtin_amdgcn_global_load_lds((const unsigned*)((const char*)(gbase) + (voff)[_i]), (LAS unsigned*)(lds + (bufoff) + ldsw + _i * 8192), 16, 0, 0); } while (0)
; #define PG8_LDA(dst, b, h) do { _Pragma("unroll") for (int m = 0; m < 4; ++m) _Pragma("unroll") for (int k = 0; k < 2; ++k) dst[m][k] = *(const LAS bf16x8*)(lds + PG8_SA(b, h) + aoff + m * 2048 + k * 1024); } while (0)
; #define PG8_LDB(dst, b, h) do { _Pragma("unroll") for (int n = 0; n < 2; ++n) _Pragma("unroll") for (int k = 0; k < 2; ++k) dst[n][k] = *(const LAS bf16x8*)(lds + PG8_SB(b, h) + boff + n * 2048 + k * 1024); } while (0)
; #define PG8_SCHED __builtin_amdgcn_sched_barrier(0)
;     __device__ __forceinline__ bool next(int i, Unit& u) const {
;         const long L = (long)i * G + c; if (L >= nwg) return false;
;         int w = (int)L; { const int q = nwg / NXCD, r = nwg % NXCD, xcd = w % NXCD, off = w / NXCD; w = (xcd < r ? xcd * (q + 1) : r * (q + 1) + (xcd - r) * q) + off; }
;         u.pb = w / per; w -= u.pb * per;
;         const int nig = WGM * nN, gid = w / nig, fm = gid * WGM, gsz = (nM - fm) < WGM ? (nM - fm) : WGM;
;         u.pm = fm + ((w % nig) % gsz); u.pn = (w % nig) / gsz; return true;
;     }
; template <class Epi>
; __device__ __forceinline__ void gemm_phase(LAS unsigned char* lds, const Gemm g, int G, int c, const Epi& E) {
;     ...
;             PG8_LDB(B0, 0, 0); PG8_LDB(B1, 0, 1); PG8_SCHED; PG8_LDA(At, 0, 0); PG8_STAGE(PG8_SA(1, 1), a1 + hstepA, voffA);
.LBB0_587:
	s_waitcnt lgkmcnt(0)
	ds_read_b128 v[142:145], v166
	ds_read_b128 v[146:149], v166 offset:1024
	ds_read_b128 v[150:153], v166 offset:2048
	ds_read_b128 v[154:157], v166 offset:3072
	ds_read_b128 v[158:161], v167
	ds_read_b128 v[170:173], v167 offset:1024
	ds_read_b128 v[174:177], v167 offset:2048
	ds_read_b128 v[178:181], v167 offset:3072
	ds_read_b128 v[182:185], v168
	ds_read_b128 v[186:189], v168 offset:1024
	ds_read_b128 v[190:193], v168 offset:2048
	ds_read_b128 v[194:197], v168 offset:3072
	ds_read_b128 v[198:201], v168 offset:4096
	ds_read_b128 v[202:205], v168 offset:5120
	ds_read_b128 v[206:209], v168 offset:6144
	ds_read_b128 v[210:213], v168 offset:7168
	s_add_i32 s90, s90, 1
	s_mul_i32 s2, s90, s70
	s_mul_hi_u32 s3, s90, s27
	s_add_i32 s3, s3, s2
	s_mul_i32 s2, s90, s27
	s_add_u32 s2, s2, s26
	s_addc_u32 s3, s3, s71
	v_cmp_gt_i64_e32 vcc, s[2:3], v[140:141]
	v_cmp_lt_i64_e64 s[4:5], s[2:3], v[138:139]
	s_cbranch_vccnz .LBB0_589
	s_ashr_i32 s3, s2, 31
	s_lshr_b32 s3, s3, 29
	s_add_i32 s3, s2, s3
	s_ashr_i32 s33, s3, 3
	s_and_b32 s3, s3, -8
	s_sub_i32 s2, s2, s3
	s_cmp_lt_i32 s2, 0
	s_cselect_b32 s3, s35, 0x48
	s_mul_i32 s2, s3, s2
	s_add_i32 s2, s2, s33
	s_mul_hi_i32 s3, s2, 0x38e38e39
	s_lshr_b32 s33, s3, 31
	s_ashr_i32 s3, s3, 2
	s_add_i32 s91, s3, s33
	s_mul_i32 s3, s91, 0xffffffee
	s_add_i32 s3, s3, s2
	s_mul_hi_i32 s2, s3, 0x38e38e39
	s_lshr_b32 s33, s2, 31
	s_ashr_i32 s2, s2, 4
	s_add_i32 s2, s2, s33
	s_lshl_b32 s33, s2, 3
	s_sub_i32 s38, 2, s33
	s_min_i32 s38, s38, 8
	s_abs_i32 s39, s38
	v_cvt_f32_u32_e32 v2, s39
	s_sub_i32 s45, 0, s39
	s_mulk_i32 s2, 0x48
	s_sub_i32 s2, s3, s2
	v_rcp_iflag_f32_e32 v2, v2
	s_abs_i32 s3, s2
	s_xor_b32 s44, s2, s38
	s_ashr_i32 s44, s44, 31
	v_mul_f32_e32 v2, 0x4f7ffffe, v2
	v_cvt_u32_f32_e32 v2, v2
	s_nop 0
	v_readfirstlane_b32 s46, v2
	s_mul_i32 s45, s45, s46
	s_mul_hi_u32 s45, s46, s45
	s_add_i32 s46, s46, s45
	s_mul_hi_u32 s45, s3, s46
	s_mul_i32 s46, s45, s39
	s_sub_i32 s3, s3, s46
	s_add_i32 s46, s45, 1
	s_sub_i32 s47, s3, s39
	s_cmp_ge_u32 s3, s39
	s_cselect_b32 s45, s46, s45
	s_cselect_b32 s3, s47, s3
	s_add_i32 s46, s45, 1
	s_cmp_ge_u32 s3, s39
	s_cselect_b32 s3, s46, s45
	s_xor_b32 s3, s3, s44
	s_sub_i32 s92, s3, s44
	s_mul_i32 s3, s92, s38
	s_sub_i32 s2, s2, s3
	s_add_i32 s93, s2, s33

; #define PG8_STAGE(bufoff, gbase, voff) do { _Pragma("unroll") for (int _i = 0; _i < 2; ++_i) \
;         __builtin_amdgcn_global_load_lds((const unsigned*)((const char*)(gbase) + (voff)[_i]), (LAS unsigned*)(lds + (bufoff) + ldsw + _i * 8192), 16, 0, 0); } while (0)
; #define PG8_LDA(dst, b, h) do { _Pragma("unroll") for (int m = 0; m < 4; ++m) _Pragma("unroll") for (int k = 0; k < 2; ++k) dst[m][k] = *(const LAS bf16x8*)(lds + PG8_SA(b, h) + aoff + m * 2048 + k * 1024); } while (0)
; #define PG8_LDB(dst, b, h) do { _Pragma("unroll") for (int n = 0; n < 2; ++n) _Pragma("unroll") for (int k = 0; k < 2; ++k) dst[n][k] = *(const LAS bf16x8*)(lds + PG8_SB(b, h) + boff + n * 2048 + k * 1024); } while (0)
; #define PG8_MMA(ai, bj, At, Bt) do { __builtin_amdgcn_s_setprio(1); _Pragma("unroll") for (int m = 0; m < 4; ++m) _Pragma("unroll") for (int n = 0; n < 2; ++n) _Pragma("unroll") for (int k = 0; k < 2; ++k) \
;         acc[ai][bj][m][n] = __builtin_amdgcn_mfma_f32_16x16x32_bf16(Bt[n][k], At[m][k], acc[ai][bj][m][n], 0, 0, 0); __builtin_amdgcn_s_setprio(0); } while (0)
; #define PG8_WAIT_V(n) asm volatile("s_waitcnt vmcnt(" #n ")" ::: "memory")
; #define PG8_WAIT_L(n) asm volatile("s_waitcnt lgkmcnt(" #n ")" ::: "memory")
; #define PG8_BAR __builtin_amdgcn_s_barrier()
; #define PG8_SCHED __builtin_amdgcn_sched_barrier(0)
; template <class Epi>
; __device__ __forceinline__ void gemm_phase(LAS unsigned char* lds, const Gemm g, int G, int c, const Epi& E) {
;     ...
;             const bool last = (t == nt - 2);
;             const char* a1 = cA + (size_t)(t + 1) * kstep;
;             const char* a2 = last ? nA : cA + (size_t)(t + 2) * kstep; const char* b2 = last ? nB : cB + (size_t)(t + 2) * kstep;
;             const char* a3 = a2 + kstep; const char* b3 = b2 + kstep;
;             PG8_LDB(B0, 0, 0); PG8_LDB(B1, 0, 1); PG8_SCHED; PG8_LDA(At, 0, 0); PG8_STAGE(PG8_SA(1, 1), a1 + hstepA, voffA);
;             PG8_WAIT_V(8); PG8_WAIT_L(0); PG8_BAR; PG8_MMA(0, 0, At, B0); PG8_MMA(0, 1, At, B1); PG8_BAR; PG8_SCHED;
;             PG8_LDA(At, 0, 1); PG8_STAGE(PG8_SB(0, 0), b2, voffB); PG8_STAGE(PG8_SB(0, 1), b2 + hstepB, voffB); PG8_STAGE(PG8_SA(0, 0), a2, voffA);
;             PG8_WAIT_V(8); PG8_WAIT_L(0); PG8_BAR; PG8_MMA(1, 0, At, B0); PG8_MMA(1, 1, At, B1); PG8_BAR; PG8_SCHED;
.LBB0_593:
	s_mov_b32 s38, 0
	s_mov_b64 s[4:5], -1
	s_mov_b64 s[54:55], 0
	s_add_u32 s33, s8, s38
	s_addc_u32 s62, s9, 0
	s_add_u32 s39, s33, 0x100
	s_addc_u32 s58, s62, 0
	s_and_b64 s[56:57], s[54:55], exec
	s_cselect_b32 s59, s45, s58
	s_cselect_b32 s58, s44, s39
	s_add_u32 s38, s6, s38
	s_addc_u32 s39, s7, 0
	s_add_u32 s56, s38, 0x100
	s_addc_u32 s57, s39, 0
	s_and_b64 s[38:39], s[54:55], exec
	s_cselect_b32 s61, s47, s57
	s_cselect_b32 s60, s46, s56
	s_add_u32 s68, s33, 0xb0080
	s_addc_u32 s69, s62, 0
	s_add_i32 s63, s86, s23
	s_add_i32 m0, s72, 0xc000
	s_add_i32 s64, s72, 0xe000
	s_add_i32 s74, s63, 0x2000
	s_add_u32 s66, s60, 0xb0000
	s_addc_u32 s67, s61, 0
	s_add_i32 s62, s87, s23
	s_add_i32 s75, s62, 0x2000
	s_add_i32 s97, 0, 0x18000
	s_add_i32 s33, 0, 0x1c000
	s_add_u32 s56, s58, 0xb0000
	s_addc_u32 s57, s59, 0
	s_add_i32 s96, s97, s23
	s_add_i32 s39, s96, 0x2000
	s_add_u32 s54, s60, 0xb0080
	s_addc_u32 s55, s61, 0
	s_add_i32 s95, s33, s23
	s_add_i32 s38, s95, 0x2000
	v_lshl_add_u64 v[162:163], s[68:69], 0, v[136:137]
	global_load_lds_dwordx4 v[162:163], off
	v_lshl_add_u64 v[162:163], s[68:69], 0, v[132:133]
	s_mov_b32 m0, s64
	s_nop 0
	global_load_lds_dwordx4 v[162:163], off
	s_waitcnt vmcnt(8)
	s_waitcnt lgkmcnt(0)
	s_barrier
	s_setprio 0
	v_mfma_f32_16x16x32_bf16 v[126:129], v[142:145], v[182:185], 0
	v_mfma_f32_16x16x32_bf16 v[122:125], v[150:153], v[182:185], 0
	v_mfma_f32_16x16x32_bf16 v[110:113], v[142:145], v[190:193], 0
	v_mfma_f32_16x16x32_bf16 v[106:109], v[150:153], v[190:193], 0
	v_mfma_f32_16x16x32_bf16 v[94:97], v[142:145], v[198:201], 0
	v_mfma_f32_16x16x32_bf16 v[90:93], v[150:153], v[198:201], 0
	v_mfma_f32_16x16x32_bf16 v[78:81], v[142:145], v[206:209], 0
	v_mfma_f32_16x16x32_bf16 v[74:77], v[150:153], v[206:209], 0
	v_mfma_f32_16x16x32_bf16 v[126:129], v[146:149], v[186:189], v[126:129]
	v_mfma_f32_16x16x32_bf16 v[122:125], v[154:157], v[186:189], v[122:125]
	v_mfma_f32_16x16x32_bf16 v[110:113], v[146:149], v[194:197], v[110:113]
	v_mfma_f32_16x16x32_bf16 v[106:109], v[154:157], v[194:197], v[106:109]
	v_mfma_f32_16x16x32_bf16 v[94:97], v[146:149], v[202:205], v[94:97]
	v_mfma_f32_16x16x32_bf16 v[90:93], v[154:157], v[202:205], v[90:93]
	v_mfma_f32_16x16x32_bf16 v[78:81], v[146:149], v[210:213], v[78:81]
	v_mfma_f32_16x16x32_bf16 v[74:77], v[154:157], v[210:213], v[74:77]
	s_setprio 2
	s_setprio 0
	v_mfma_f32_16x16x32_bf16 v[118:121], v[158:161], v[182:185], 0
	v_mfma_f32_16x16x32_bf16 v[114:117], v[174:177], v[182:185], 0
	v_mfma_f32_16x16x32_bf16 v[102:105], v[158:161], v[190:193], 0
	v_mfma_f32_16x16x32_bf16 v[98:101], v[174:177], v[190:193], 0
	v_mfma_f32_16x16x32_bf16 v[86:89], v[158:161], v[198:201], 0
	v_mfma_f32_16x16x32_bf16 v[82:85], v[174:177], v[198:201], 0
	v_mfma_f32_16x16x32_bf16 v[70:73], v[158:161], v[206:209], 0
	v_mfma_f32_16x16x32_bf16 v[66:69], v[174:177], v[206:209], 0
	v_mfma_f32_16x16x32_bf16 v[118:121], v[170:173], v[186:189], v[118:121]
	v_mfma_f32_16x16x32_bf16 v[114:117], v[178:181], v[186:189], v[114:117]
	v_mfma_f32_16x16x32_bf16 v[102:105], v[170:173], v[194:197], v[102:105]
	v_mfma_f32_16x16x32_bf16 v[98:101], v[178:181], v[194:197], v[98:101]
	v_mfma_f32_16x16x32_bf16 v[86:89], v[170:173], v[202:205], v[86:89]
	v_mfma_f32_16x16x32_bf16 v[82:85], v[178:181], v[202:205], v[82:85]
	v_mfma_f32_16x16x32_bf16 v[70:73], v[170:173], v[210:213], v[70:73]
	v_mfma_f32_16x16x32_bf16 v[66:69], v[178:181], v[210:213], v[66:69]
	s_setprio 2
	s_barrier
	s_mov_b32 m0, s63
	v_lshl_add_u64 v[162:163], s[60:61], 0, v[134:135]
	ds_read_b128 v[182:185], v168 offset:16384
	ds_read_b128 v[186:189], v168 offset:17408
	ds_read_b128 v[190:193], v168 offset:18432
	ds_read_b128 v[194:197], v168 offset:19456
	ds_read_b128 v[198:201], v168 offset:20480
	ds_read_b128 v[202:205], v168 offset:21504
	ds_read_b128 v[206:209], v168 offset:22528
	ds_read_b128 v[210:213], v168 offset:23552
	global_load_lds_dwordx4 v[162:163], off
	v_lshl_add_u64 v[214:215], s[60:61], 0, v[130:131]
	s_mov_b32 m0, s74
	v_lshl_add_u64 v[216:217], s[66:67], 0, v[134:135]
	global_load_lds_dwordx4 v[214:215], off
	s_mov_b32 m0, s62
	v_lshl_add_u64 v[218:219], s[58:59], 0, v[132:133]
	global_load_lds_dwordx4 v[216:217], off
	v_lshl_add_u64 v[216:217], s[66:67], 0, v[130:131]
	s_mov_b32 m0, s75
	s_nop 0
	global_load_lds_dwordx4 v[216:217], off
	v_lshl_add_u64 v[216:217], s[58:59], 0, v[136:137]
	s_mov_b32 m0, s72
	s_nop 0
	global_load_lds_dwordx4 v[216:217], off
	s_mov_b32 m0, s73
	s_nop 0
	global_load_lds_dwordx4 v[218:219], off
	s_waitcnt vmcnt(8)
	s_waitcnt lgkmcnt(0)
	s_barrier
	s_setprio 0
	v_mfma_f32_16x16x32_bf16 v[62:65], v[142:145], v[182:185], 0
	v_mfma_f32_16x16x32_bf16 v[58:61], v[150:153], v[182:185], 0
	v_mfma_f32_16x16x32_bf16 v[46:49], v[142:145], v[190:193], 0
	v_mfma_f32_16x16x32_bf16 v[42:45], v[150:153], v[190:193], 0
	v_mfma_f32_16x16x32_bf16 v[30:33], v[142:145], v[198:201], 0
	v_mfma_f32_16x16x32_bf16 v[26:29], v[150:153], v[198:201], 0
	v_mfma_f32_16x16x32_bf16 v[14:17], v[142:145], v[206:209], 0
	v_mfma_f32_16x16x32_bf16 v[10:13], v[150:153], v[206:209], 0
	v_mfma_f32_16x16x32_bf16 v[62:65], v[146:149], v[186:189], v[62:65]
	v_mfma_f32_16x16x32_bf16 v[58:61], v[154:157], v[186:189], v[58:61]
	v_mfma_f32_16x16x32_bf16 v[46:49], v[146:149], v[194:197], v[46:49]
	v_mfma_f32_16x16x32_bf16 v[42:45], v[154:157], v[194:197], v[42:45]
	v_mfma_f32_16x16x32_bf16 v[30:33], v[146:149], v[202:205], v[30:33]
	v_mfma_f32_16x16x32_bf16 v[26:29], v[154:157], v[202:205], v[26:29]
	v_mfma_f32_16x16x32_bf16 v[14:17], v[146:149], v[210:213], v[14:17]
	v_mfma_f32_16x16x32_bf16 v[10:13], v[154:157], v[210:213], v[10:13]
	s_setprio 2
	s_setprio 0
	v_mfma_f32_16x16x32_bf16 v[54:57], v[158:161], v[182:185], 0
	v_mfma_f32_16x16x32_bf16 v[50:53], v[174:177], v[182:185], 0
	v_mfma_f32_16x16x32_bf16 v[38:41], v[158:161], v[190:193], 0
	v_mfma_f32_16x16x32_bf16 v[34:37], v[174:177], v[190:193], 0
	v_mfma_f32_16x16x32_bf16 v[22:25], v[158:161], v[198:201], 0
	v_mfma_f32_16x16x32_bf16 v[18:21], v[174:177], v[198:201], 0
	v_mfma_f32_16x16x32_bf16 v[6:9], v[158:161], v[206:209], 0
	v_mfma_f32_16x16x32_bf16 v[2:5], v[174:177], v[206:209], 0
	v_mfma_f32_16x16x32_bf16 v[54:57], v[170:173], v[186:189], v[54:57]
	v_mfma_f32_16x16x32_bf16 v[50:53], v[178:181], v[186:189], v[50:53]
	v_mfma_f32_16x16x32_bf16 v[38:41], v[170:173], v[194:197], v[38:41]
	v_mfma_f32_16x16x32_bf16 v[34:37], v[178:181], v[194:197], v[34:37]
	v_mfma_f32_16x16x32_bf16 v[22:25], v[170:173], v[202:205], v[22:25]
	v_mfma_f32_16x16x32_bf16 v[18:21], v[178:181], v[202:205], v[18:21]
	v_mfma_f32_16x16x32_bf16 v[6:9], v[170:173], v[210:213], v[6:9]
	v_mfma_f32_16x16x32_bf16 v[2:5], v[178:181], v[210:213], v[2:5]
	s_setprio 2
	s_barrier
; #define PG8_STAGE(bufoff, gbase, voff) do { _Pragma("unroll") for (int _i = 0; _i < 2; ++_i) \
;         __builtin_amdgcn_global_load_lds((const unsigned*)((const char*)(gbase) + (voff)[_i]), (LAS unsigned*)(lds + (bufoff) + ldsw + _i * 8192), 16, 0, 0); } while (0)
; #define PG8_LDA(dst, b, h) do { _Pragma("unroll") for (int m = 0; m < 4; ++m) _Pragma("unroll") for (int k = 0; k < 2; ++k) dst[m][k] = *(const LAS bf16x8*)(lds + PG8_SA(b, h) + aoff + m * 2048 + k * 1024); } while (0)
; #define PG8_LDB(dst, b, h) do { _Pragma("unroll") for (int n = 0; n < 2; ++n) _Pragma("unroll") for (int k = 0; k < 2; ++k) dst[n][k] = *(const LAS bf16x8*)(lds + PG8_SB(b, h) + boff + n * 2048 + k * 1024); } while (0)
; #define PG8_MMA(ai, bj, At, Bt) do { __builtin_amdgcn_s_setprio(1); _Pragma("unroll") for (int m = 0; m < 4; ++m) _Pragma("unroll") for (int n = 0; n < 2; ++n) _Pragma("unroll") for (int k = 0; k < 2; ++k) \
;         acc[ai][bj][m][n] = __builtin_amdgcn_mfma_f32_16x16x32_bf16(Bt[n][k], At[m][k], acc[ai][bj][m][n], 0, 0, 0); __builtin_amdgcn_s_setprio(0); } while (0)
; #define PG8_WAIT_V(n) asm volatile("s_waitcnt vmcnt(" #n ")" ::: "memory")
; #define PG8_WAIT_L(n) asm volatile("s_waitcnt lgkmcnt(" #n ")" ::: "memory")
; #define PG8_BAR __builtin_amdgcn_s_barrier()
; #define PG8_SCHED __builtin_amdgcn_sched_barrier(0)
; template <class Epi>
; __device__ __forceinline__ void gemm_phase(LAS unsigned char* lds, const Gemm g, int G, int c, const Epi& E) {
;     ...
;             PG8_LDB(B0, 1, 0); PG8_LDB(B1, 1, 1); PG8_SCHED; PG8_LDA(At, 1, 0); PG8_STAGE(PG8_SA(0, 1), a2 + hstepA, voffA);
;             PG8_WAIT_V(8); PG8_WAIT_L(0); PG8_BAR; PG8_MMA(0, 0, At, B0); PG8_MMA(0, 1, At, B1); PG8_BAR; PG8_SCHED;
;             PG8_LDA(At, 1, 1); PG8_STAGE(PG8_SB(1, 0), b3, voffB); PG8_STAGE(PG8_SB(1, 1), b3 + hstepB, voffB); PG8_STAGE(PG8_SA(1, 0), a3, voffA);
;             PG8_WAIT_V(8); PG8_WAIT_L(0); PG8_BAR; PG8_MMA(1, 0, At, B0); PG8_MMA(1, 1, At, B1); PG8_BAR; PG8_SCHED;
;         }
	v_add_u32_e32 v154, s97, v165
	v_add_u32_e32 v178, s33, v165
	ds_read_b128 v[142:145], v154
	ds_read_b128 v[146:149], v154 offset:1024
	ds_read_b128 v[150:153], v154 offset:2048
	ds_read_b128 v[154:157], v154 offset:3072
	ds_read_b128 v[158:161], v178
	ds_read_b128 v[170:173], v178 offset:1024
	ds_read_b128 v[174:177], v178 offset:2048
	ds_read_b128 v[178:181], v178 offset:3072
	s_mov_b32 m0, s78
	v_lshl_add_u64 v[220:221], s[56:57], 0, v[136:137]
	ds_read_b128 v[182:185], v168 offset:32768
	ds_read_b128 v[186:189], v168 offset:33792
	ds_read_b128 v[190:193], v168 offset:34816
	ds_read_b128 v[194:197], v168 offset:35840
	ds_read_b128 v[198:201], v168 offset:36864
	ds_read_b128 v[202:205], v168 offset:37888
	ds_read_b128 v[206:209], v168 offset:38912
	ds_read_b128 v[210:213], v168 offset:39936
	global_load_lds_dwordx4 v[220:221], off
	v_lshl_add_u64 v[220:221], s[56:57], 0, v[132:133]
	s_mov_b32 m0, s81
	s_nop 0
	global_load_lds_dwordx4 v[220:221], off
	s_waitcnt vmcnt(8)
	s_waitcnt lgkmcnt(0)
	s_barrier
	s_setprio 0
	v_mfma_f32_16x16x32_bf16 v[126:129], v[142:145], v[182:185], v[126:129]
	v_mfma_f32_16x16x32_bf16 v[122:125], v[150:153], v[182:185], v[122:125]
	v_mfma_f32_16x16x32_bf16 v[110:113], v[142:145], v[190:193], v[110:113]
	v_mfma_f32_16x16x32_bf16 v[106:109], v[150:153], v[190:193], v[106:109]
	v_mfma_f32_16x16x32_bf16 v[94:97], v[142:145], v[198:201], v[94:97]
	v_mfma_f32_16x16x32_bf16 v[90:93], v[150:153], v[198:201], v[90:93]
	v_mfma_f32_16x16x32_bf16 v[78:81], v[142:145], v[206:209], v[78:81]
	v_mfma_f32_16x16x32_bf16 v[74:77], v[150:153], v[206:209], v[74:77]
	v_mfma_f32_16x16x32_bf16 v[126:129], v[146:149], v[186:189], v[126:129]
	v_mfma_f32_16x16x32_bf16 v[122:125], v[154:157], v[186:189], v[122:125]
	v_mfma_f32_16x16x32_bf16 v[110:113], v[146:149], v[194:197], v[110:113]
	v_mfma_f32_16x16x32_bf16 v[106:109], v[154:157], v[194:197], v[106:109]
	v_mfma_f32_16x16x32_bf16 v[94:97], v[146:149], v[202:205], v[94:97]
	v_mfma_f32_16x16x32_bf16 v[90:93], v[154:157], v[202:205], v[90:93]
	v_mfma_f32_16x16x32_bf16 v[78:81], v[146:149], v[210:213], v[78:81]
	v_mfma_f32_16x16x32_bf16 v[74:77], v[154:157], v[210:213], v[74:77]
	s_setprio 2
	s_setprio 0
	v_mfma_f32_16x16x32_bf16 v[118:121], v[158:161], v[182:185], v[118:121]
	v_mfma_f32_16x16x32_bf16 v[114:117], v[174:177], v[182:185], v[114:117]
	v_mfma_f32_16x16x32_bf16 v[102:105], v[158:161], v[190:193], v[102:105]
	v_mfma_f32_16x16x32_bf16 v[98:101], v[174:177], v[190:193], v[98:101]
	v_mfma_f32_16x16x32_bf16 v[86:89], v[158:161], v[198:201], v[86:89]
	v_mfma_f32_16x16x32_bf16 v[82:85], v[174:177], v[198:201], v[82:85]
	v_mfma_f32_16x16x32_bf16 v[70:73], v[158:161], v[206:209], v[70:73]
	v_mfma_f32_16x16x32_bf16 v[66:69], v[174:177], v[206:209], v[66:69]
	v_mfma_f32_16x16x32_bf16 v[118:121], v[170:173], v[186:189], v[118:121]
	v_mfma_f32_16x16x32_bf16 v[114:117], v[178:181], v[186:189], v[114:117]
	v_mfma_f32_16x16x32_bf16 v[102:105], v[170:173], v[194:197], v[102:105]
	v_mfma_f32_16x16x32_bf16 v[98:101], v[178:181], v[194:197], v[98:101]
	v_mfma_f32_16x16x32_bf16 v[86:89], v[170:173], v[202:205], v[86:89]
	v_mfma_f32_16x16x32_bf16 v[82:85], v[178:181], v[202:205], v[82:85]
	v_mfma_f32_16x16x32_bf16 v[70:73], v[170:173], v[210:213], v[70:73]
	v_mfma_f32_16x16x32_bf16 v[66:69], v[178:181], v[210:213], v[66:69]
	s_setprio 2
	s_barrier
	s_mov_b32 m0, s96
	v_lshl_add_u64 v[162:163], v[162:163], 0, s[18:19]
	ds_read_b128 v[182:185], v168 offset:49152
	ds_read_b128 v[186:189], v168 offset:50176
	ds_read_b128 v[190:193], v168 offset:51200
	ds_read_b128 v[194:197], v168 offset:52224
	ds_read_b128 v[198:201], v168 offset:53248
	ds_read_b128 v[202:205], v168 offset:54272
	ds_read_b128 v[206:209], v168 offset:55296
	ds_read_b128 v[210:213], v168 offset:56320
	global_load_lds_dwordx4 v[162:163], off
	v_lshl_add_u64 v[162:163], v[214:215], 0, s[18:19]
	s_mov_b32 m0, s39
	s_nop 0
	global_load_lds_dwordx4 v[162:163], off
	v_lshl_add_u64 v[162:163], s[54:55], 0, v[134:135]
	s_mov_b32 m0, s95
	s_nop 0
	global_load_lds_dwordx4 v[162:163], off
	v_lshl_add_u64 v[162:163], s[54:55], 0, v[130:131]
	s_mov_b32 m0, s38
	s_nop 0
	global_load_lds_dwordx4 v[162:163], off
	v_lshl_add_u64 v[162:163], v[216:217], 0, s[18:19]
	s_mov_b32 m0, s84
	s_nop 0
	global_load_lds_dwordx4 v[162:163], off
	v_lshl_add_u64 v[162:163], v[218:219], 0, s[18:19]
	s_mov_b32 m0, s85
	s_nop 0
	global_load_lds_dwordx4 v[162:163], off
	s_waitcnt vmcnt(8)
	s_waitcnt lgkmcnt(0)
	s_barrier
	s_setprio 0
	v_mfma_f32_16x16x32_bf16 v[62:65], v[142:145], v[182:185], v[62:65]
	v_mfma_f32_16x16x32_bf16 v[58:61], v[150:153], v[182:185], v[58:61]
	v_mfma_f32_16x16x32_bf16 v[46:49], v[142:145], v[190:193], v[46:49]
	v_mfma_f32_16x16x32_bf16 v[42:45], v[150:153], v[190:193], v[42:45]
	v_mfma_f32_16x16x32_bf16 v[30:33], v[142:145], v[198:201], v[30:33]
	v_mfma_f32_16x16x32_bf16 v[26:29], v[150:153], v[198:201], v[26:29]
	v_mfma_f32_16x16x32_bf16 v[14:17], v[142:145], v[206:209], v[14:17]
	v_mfma_f32_16x16x32_bf16 v[10:13], v[150:153], v[206:209], v[10:13]
	v_mfma_f32_16x16x32_bf16 v[62:65], v[146:149], v[186:189], v[62:65]
	v_mfma_f32_16x16x32_bf16 v[58:61], v[154:157], v[186:189], v[58:61]
	v_mfma_f32_16x16x32_bf16 v[46:49], v[146:149], v[194:197], v[46:49]
	v_mfma_f32_16x16x32_bf16 v[42:45], v[154:157], v[194:197], v[42:45]
	v_mfma_f32_16x16x32_bf16 v[30:33], v[146:149], v[202:205], v[30:33]
	v_mfma_f32_16x16x32_bf16 v[26:29], v[154:157], v[202:205], v[26:29]
	v_mfma_f32_16x16x32_bf16 v[14:17], v[146:149], v[210:213], v[14:17]
	v_mfma_f32_16x16x32_bf16 v[10:13], v[154:157], v[210:213], v[10:13]
	s_setprio 2
	s_setprio 0
	v_mfma_f32_16x16x32_bf16 v[54:57], v[158:161], v[182:185], v[54:57]
	v_mfma_f32_16x16x32_bf16 v[50:53], v[174:177], v[182:185], v[50:53]
	v_mfma_f32_16x16x32_bf16 v[38:41], v[158:161], v[190:193], v[38:41]
	v_mfma_f32_16x16x32_bf16 v[34:37], v[174:177], v[190:193], v[34:37]
	v_mfma_f32_16x16x32_bf16 v[22:25], v[158:161], v[198:201], v[22:25]
	v_mfma_f32_16x16x32_bf16 v[18:21], v[174:177], v[198:201], v[18:21]
	v_mfma_f32_16x16x32_bf16 v[6:9], v[158:161], v[206:209], v[6:9]
	v_mfma_f32_16x16x32_bf16 v[2:5], v[174:177], v[206:209], v[2:5]
	v_mfma_f32_16x16x32_bf16 v[54:57], v[170:173], v[186:189], v[54:57]
	v_mfma_f32_16x16x32_bf16 v[50:53], v[178:181], v[186:189], v[50:53]
	v_mfma_f32_16x16x32_bf16 v[38:41], v[170:173], v[194:197], v[38:41]
	v_mfma_f32_16x16x32_bf16 v[34:37], v[178:181], v[194:197], v[34:37]
	v_mfma_f32_16x16x32_bf16 v[22:25], v[170:173], v[202:205], v[22:25]
	v_mfma_f32_16x16x32_bf16 v[18:21], v[178:181], v[202:205], v[18:21]
	v_mfma_f32_16x16x32_bf16 v[6:9], v[170:173], v[210:213], v[6:9]
	v_mfma_f32_16x16x32_bf16 v[2:5], v[178:181], v[210:213], v[2:5]
	s_setprio 2
	s_barrier
	s_movk_i32 s38, 0x100
	s_andn2_b64 vcc, exec, s[4:5]
	s_mov_b64 s[54:55], -1
	s_mov_b64 s[4:5], 0
	s_cbranch_vccz .LBB0_594

; #define PG8_STAGE(bufoff, gbase, voff) do { _Pragma("unroll") for (int _i = 0; _i < 2; ++_i) \
;         __builtin_amdgcn_global_load_lds((const unsigned*)((const char*)(gbase) + (voff)[_i]), (LAS unsigned*)(lds + (bufoff) + ldsw + _i * 8192), 16, 0, 0); } while (0)
; #define PG8_LDA(dst, b, h) do { _Pragma("unroll") for (int m = 0; m < 4; ++m) _Pragma("unroll") for (int k = 0; k < 2; ++k) dst[m][k] = *(const LAS bf16x8*)(lds + PG8_SA(b, h) + aoff + m * 2048 + k * 1024); } while (0)
; #define PG8_LDB(dst, b, h) do { _Pragma("unroll") for (int n = 0; n < 2; ++n) _Pragma("unroll") for (int k = 0; k < 2; ++k) dst[n][k] = *(const LAS bf16x8*)(lds + PG8_SB(b, h) + boff + n * 2048 + k * 1024); } while (0)
; #define PG8_SCHED __builtin_amdgcn_sched_barrier(0)
;     __device__ __forceinline__ bool next(int i, Unit& u) const {
;         const long L = (long)i * G + c; if (L >= nwg) return false;
;         int w = (int)L; { const int q = nwg / NXCD, r = nwg % NXCD, xcd = w % NXCD, off = w / NXCD; w = (xcd < r ? xcd * (q + 1) : r * (q + 1) + (xcd - r) * q) + off; }
;         u.pb = w / per; w -= u.pb * per;
;         const int nig = WGM * nN, gid = w / nig, fm = gid * WGM, gsz = (nM - fm) < WGM ? (nM - fm) : WGM;
;         u.pm = fm + ((w % nig) % gsz); u.pn = (w % nig) / gsz; return true;
;     }
; template <class Epi>
; __device__ __forceinline__ void gemm_phase(LAS unsigned char* lds, const Gemm g, int G, int c, const Epi& E) {
;     ...
;             PG8_LDB(B0, 0, 0); PG8_LDB(B1, 0, 1); PG8_SCHED; PG8_LDA(At, 0, 0); PG8_STAGE(PG8_SA(1, 1), a1 + hstepA, voffA);
.LBB0_1292:
	s_waitcnt lgkmcnt(0)
	ds_read_b128 v[146:149], v152
	ds_read_b128 v[158:161], v152 offset:1024
	ds_read_b128 v[162:165], v152 offset:2048
	ds_read_b128 v[166:169], v152 offset:3072
	ds_read_b128 v[170:173], v153
	ds_read_b128 v[174:177], v153 offset:1024
	ds_read_b128 v[178:181], v153 offset:2048
	ds_read_b128 v[182:185], v153 offset:3072
	ds_read_b128 v[186:189], v154
	ds_read_b128 v[190:193], v154 offset:1024
	ds_read_b128 v[194:197], v154 offset:2048
	ds_read_b128 v[198:201], v154 offset:3072
	ds_read_b128 v[202:205], v154 offset:4096
	ds_read_b128 v[206:209], v154 offset:5120
	ds_read_b128 v[210:213], v154 offset:6144
	ds_read_b128 v[214:217], v154 offset:7168
	s_add_i32 s78, s78, 1
	s_mul_i32 s2, s78, s35
	s_mul_hi_u32 s3, s78, s27
	s_add_i32 s3, s3, s2
	s_mul_i32 s2, s78, s27
	s_add_u32 s2, s2, s26
	s_addc_u32 s3, s3, s34
	v_cmp_gt_i64_e32 vcc, s[2:3], v[144:145]
	v_cmp_lt_i64_e64 s[4:5], s[2:3], v[142:143]
	s_cbranch_vccnz .LBB0_1294
	s_ashr_i32 s3, s2, 31
	s_lshr_b32 s3, s3, 29
	s_add_i32 s3, s2, s3
	s_ashr_i32 s7, s3, 3
	s_and_b32 s3, s3, -8
	s_sub_i32 s2, s2, s3
	s_cmp_lt_i32 s2, 0
	s_cselect_b32 s3, s70, 0x18c
	s_mul_i32 s2, s3, s2
	s_add_i32 s2, s2, s7
	s_mul_hi_i32 s3, s2, 0xa57eb503
	s_add_i32 s3, s3, s2
	s_lshr_b32 s7, s3, 31
	s_ashr_i32 s3, s3, 6
	s_add_i32 s79, s3, s7
	s_mul_i32 s3, s79, 0xffffff9d
	s_add_i32 s3, s3, s2
	s_mul_hi_i32 s2, s3, 0x2e8ba2e9
	s_lshr_b32 s7, s2, 31
	s_ashr_i32 s2, s2, 4
	s_add_i32 s2, s2, s7
	s_lshl_b32 s7, s2, 3
	s_sub_i32 s33, 9, s7
	s_min_i32 s33, s33, 8
	s_abs_i32 s38, s33
	v_cvt_f32_u32_e32 v2, s38
	s_sub_i32 s40, 0, s38
	s_mulk_i32 s2, 0x58
	s_sub_i32 s2, s3, s2
	v_rcp_iflag_f32_e32 v2, v2
	s_abs_i32 s3, s2
	s_xor_b32 s39, s2, s33
	s_ashr_i32 s39, s39, 31
	v_mul_f32_e32 v2, 0x4f7ffffe, v2
	v_cvt_u32_f32_e32 v2, v2
	s_nop 0
	v_readfirstlane_b32 s41, v2
	s_mul_i32 s40, s40, s41
	s_mul_hi_u32 s40, s41, s40
	s_add_i32 s41, s41, s40
	s_mul_hi_u32 s40, s3, s41
	s_mul_i32 s41, s40, s38
	s_sub_i32 s3, s3, s41
	s_add_i32 s41, s40, 1
	s_sub_i32 s42, s3, s38
	s_cmp_ge_u32 s3, s38
	s_cselect_b32 s40, s41, s40
	s_cselect_b32 s3, s42, s3
	s_add_i32 s41, s40, 1
	s_cmp_ge_u32 s3, s38
	s_cselect_b32 s3, s41, s40
	s_xor_b32 s3, s3, s39
	s_sub_i32 s38, s3, s39
	s_mul_i32 s3, s38, s33
	s_sub_i32 s2, s2, s3
	s_add_i32 s40, s2, s7

; #define PG8_STAGE(bufoff, gbase, voff) do { _Pragma("unroll") for (int _i = 0; _i < 2; ++_i) \
;         __builtin_amdgcn_global_load_lds((const unsigned*)((const char*)(gbase) + (voff)[_i]), (LAS unsigned*)(lds + (bufoff) + ldsw + _i * 8192), 16, 0, 0); } while (0)
; #define PG8_LDA(dst, b, h) do { _Pragma("unroll") for (int m = 0; m < 4; ++m) _Pragma("unroll") for (int k = 0; k < 2; ++k) dst[m][k] = *(const LAS bf16x8*)(lds + PG8_SA(b, h) + aoff + m * 2048 + k * 1024); } while (0)
; #define PG8_LDB(dst, b, h) do { _Pragma("unroll") for (int n = 0; n < 2; ++n) _Pragma("unroll") for (int k = 0; k < 2; ++k) dst[n][k] = *(const LAS bf16x8*)(lds + PG8_SB(b, h) + boff + n * 2048 + k * 1024); } while (0)
; #define PG8_MMA(ai, bj, At, Bt) do { __builtin_amdgcn_s_setprio(1); _Pragma("unroll") for (int m = 0; m < 4; ++m) _Pragma("unroll") for (int n = 0; n < 2; ++n) _Pragma("unroll") for (int k = 0; k < 2; ++k) \
;         acc[ai][bj][m][n] = __builtin_amdgcn_mfma_f32_16x16x32_bf16(Bt[n][k], At[m][k], acc[ai][bj][m][n], 0, 0, 0); __builtin_amdgcn_s_setprio(0); } while (0)
; #define PG8_BAR __builtin_amdgcn_s_barrier()
; template <class Epi>
; __device__ __forceinline__ void gemm_phase(LAS unsigned char* lds, const Gemm g, int G, int c, const Epi& E) {
;     ...
;         const char* nA = has_next ? (const char*)(g.A + (size_t)nxt.pb * g.sA) + (size_t)nxt.pm * 2 * hstepA : cA;
;         const char* nB = has_next ? (const char*)(g.Bt + (size_t)nxt.pb * g.sB) + (size_t)nxt.pn * 2 * hstepB : cB;
; #pragma nounroll
;         for (int t = 0; t < nt; t += 2) {
;             const bool last = (t == nt - 2);
;             const char* a1 = cA + (size_t)(t + 1) * kstep;
;             const char* a2 = last ? nA : cA + (size_t)(t + 2) * kstep; const char* b2 = last ? nB : cB + (size_t)(t + 2) * kstep;
;             const char* a3 = a2 + kstep; const char* b3 = b2 + kstep;
;             PG8_LDB(B0, 0, 0); PG8_LDB(B1, 0, 1); PG8_SCHED; PG8_LDA(At, 0, 0); PG8_STAGE(PG8_SA(1, 1), a1 + hstepA, voffA);
;             PG8_WAIT_V(8); PG8_WAIT_L(0); PG8_BAR; PG8_MMA(0, 0, At, B0); PG8_MMA(0, 1, At, B1); PG8_BAR; PG8_SCHED;
;             PG8_LDA(At, 0, 1); PG8_STAGE(PG8_SB(0, 0), b2, voffB); PG8_STAGE(PG8_SB(0, 1), b2 + hstepB, voffB); PG8_STAGE(PG8_SA(0, 0), a2, voffA);
;             PG8_WAIT_V(8); PG8_WAIT_L(0); PG8_BAR; PG8_MMA(1, 0, At, B0); PG8_MMA(1, 1, At, B1); PG8_BAR; PG8_SCHED;
.LBB0_1296:
	s_ashr_i32 s39, s38, 31
	s_lshl_b64 s[44:45], s[38:39], 19
	s_add_u32 s44, s54, s44
	s_addc_u32 s45, s55, s45
	s_and_b64 s[4:5], s[4:5], exec
	s_cselect_b32 s7, s45, s47
	s_cselect_b32 s39, s44, s46
	s_add_u32 s4, s48, 0x40080
	s_addc_u32 s5, s49, 0
	s_add_u32 s41, s46, 0x100
	s_addc_u32 s80, s47, 0
	s_mov_b32 s81, -2
	s_add_u32 s33, s4, 0xfffc0080
	s_addc_u32 s46, s5, -1
	s_cmp_eq_u32 s81, 12
	s_cselect_b32 s49, s43, s46
	s_cselect_b32 s48, s42, s33
	s_cselect_b32 s47, s7, s80
	s_cselect_b32 s46, s39, s41
	v_lshl_add_u64 v[218:219], s[4:5], 0, v[138:139]
	s_add_i32 m0, s11, 0xc000
	global_load_lds_dwordx4 v[218:219], off
	v_lshl_add_u64 v[218:219], s[4:5], 0, v[140:141]
	s_add_i32 m0, s11, 0xe000
	s_nop 0
	global_load_lds_dwordx4 v[218:219], off
	s_waitcnt vmcnt(8)
	s_waitcnt lgkmcnt(0)
	s_barrier
	s_setprio 0
	v_mfma_f32_16x16x32_bf16 v[126:129], v[146:149], v[186:189], 0
	v_mfma_f32_16x16x32_bf16 v[122:125], v[162:165], v[186:189], 0
	v_mfma_f32_16x16x32_bf16 v[110:113], v[146:149], v[194:197], 0
	v_mfma_f32_16x16x32_bf16 v[106:109], v[162:165], v[194:197], 0
	v_mfma_f32_16x16x32_bf16 v[94:97], v[146:149], v[202:205], 0
	v_mfma_f32_16x16x32_bf16 v[90:93], v[162:165], v[202:205], 0
	v_mfma_f32_16x16x32_bf16 v[78:81], v[146:149], v[210:213], 0
	v_mfma_f32_16x16x32_bf16 v[74:77], v[162:165], v[210:213], 0
	v_mfma_f32_16x16x32_bf16 v[126:129], v[158:161], v[190:193], v[126:129]
	v_mfma_f32_16x16x32_bf16 v[122:125], v[166:169], v[190:193], v[122:125]
	v_mfma_f32_16x16x32_bf16 v[110:113], v[158:161], v[198:201], v[110:113]
	v_mfma_f32_16x16x32_bf16 v[106:109], v[166:169], v[198:201], v[106:109]
	v_mfma_f32_16x16x32_bf16 v[94:97], v[158:161], v[206:209], v[94:97]
	v_mfma_f32_16x16x32_bf16 v[90:93], v[166:169], v[206:209], v[90:93]
	v_mfma_f32_16x16x32_bf16 v[78:81], v[158:161], v[214:217], v[78:81]
	v_mfma_f32_16x16x32_bf16 v[74:77], v[166:169], v[214:217], v[74:77]
	s_setprio 2
	s_setprio 0
	v_mfma_f32_16x16x32_bf16 v[118:121], v[170:173], v[186:189], 0
	v_mfma_f32_16x16x32_bf16 v[114:117], v[178:181], v[186:189], 0
	v_mfma_f32_16x16x32_bf16 v[102:105], v[170:173], v[194:197], 0
	v_mfma_f32_16x16x32_bf16 v[98:101], v[178:181], v[194:197], 0
	v_mfma_f32_16x16x32_bf16 v[86:89], v[170:173], v[202:205], 0
	v_mfma_f32_16x16x32_bf16 v[82:85], v[178:181], v[202:205], 0
	v_mfma_f32_16x16x32_bf16 v[70:73], v[170:173], v[210:213], 0
	v_mfma_f32_16x16x32_bf16 v[66:69], v[178:181], v[210:213], 0
	v_mfma_f32_16x16x32_bf16 v[118:121], v[174:177], v[190:193], v[118:121]
	v_mfma_f32_16x16x32_bf16 v[114:117], v[182:185], v[190:193], v[114:117]
	v_mfma_f32_16x16x32_bf16 v[102:105], v[174:177], v[198:201], v[102:105]
	v_mfma_f32_16x16x32_bf16 v[98:101], v[182:185], v[198:201], v[98:101]
	v_mfma_f32_16x16x32_bf16 v[86:89], v[174:177], v[206:209], v[86:89]
	v_mfma_f32_16x16x32_bf16 v[82:85], v[182:185], v[206:209], v[82:85]
	v_mfma_f32_16x16x32_bf16 v[70:73], v[174:177], v[214:217], v[70:73]
	v_mfma_f32_16x16x32_bf16 v[66:69], v[182:185], v[214:217], v[66:69]
	s_setprio 2
	s_barrier
	s_add_i32 s33, s71, s56
	v_lshl_add_u64 v[218:219], s[46:47], 0, v[132:133]
	s_mov_b32 m0, s33
	ds_read_b128 v[186:189], v154 offset:16384
	ds_read_b128 v[190:193], v154 offset:17408
	ds_read_b128 v[194:197], v154 offset:18432
	ds_read_b128 v[198:201], v154 offset:19456
	ds_read_b128 v[202:205], v154 offset:20480
	ds_read_b128 v[206:209], v154 offset:21504
	ds_read_b128 v[210:213], v154 offset:22528
	ds_read_b128 v[214:217], v154 offset:23552
	global_load_lds_dwordx4 v[218:219], off
	s_add_i32 m0, s33, 0x2000
	s_add_u32 s62, s46, 0x40000
	v_lshl_add_u64 v[220:221], s[46:47], 0, v[136:137]
	s_addc_u32 s63, s47, 0
	s_add_i32 s33, s72, s56
	global_load_lds_dwordx4 v[220:221], off
	v_lshl_add_u64 v[222:223], s[62:63], 0, v[132:133]
	s_mov_b32 m0, s33
	v_lshl_add_u64 v[224:225], s[48:49], 0, v[134:135]
	global_load_lds_dwordx4 v[222:223], off
	v_lshl_add_u64 v[222:223], s[62:63], 0, v[136:137]
	s_add_i32 m0, s33, 0x2000
	s_nop 0
	global_load_lds_dwordx4 v[222:223], off
	v_lshl_add_u64 v[222:223], s[48:49], 0, v[130:131]
	s_mov_b32 m0, s11
	s_nop 0
	global_load_lds_dwordx4 v[222:223], off
	s_mov_b32 m0, s57
	s_nop 0
	global_load_lds_dwordx4 v[224:225], off
	s_waitcnt vmcnt(8)
	s_waitcnt lgkmcnt(0)
	s_barrier
	s_setprio 0
	v_mfma_f32_16x16x32_bf16 v[62:65], v[146:149], v[186:189], 0
	v_mfma_f32_16x16x32_bf16 v[58:61], v[162:165], v[186:189], 0
	v_mfma_f32_16x16x32_bf16 v[46:49], v[146:149], v[194:197], 0
	v_mfma_f32_16x16x32_bf16 v[42:45], v[162:165], v[194:197], 0
	v_mfma_f32_16x16x32_bf16 v[30:33], v[146:149], v[202:205], 0
	v_mfma_f32_16x16x32_bf16 v[26:29], v[162:165], v[202:205], 0
	v_mfma_f32_16x16x32_bf16 v[14:17], v[146:149], v[210:213], 0
	v_mfma_f32_16x16x32_bf16 v[10:13], v[162:165], v[210:213], 0
	v_mfma_f32_16x16x32_bf16 v[62:65], v[158:161], v[190:193], v[62:65]
	v_mfma_f32_16x16x32_bf16 v[58:61], v[166:169], v[190:193], v[58:61]
	v_mfma_f32_16x16x32_bf16 v[46:49], v[158:161], v[198:201], v[46:49]
	v_mfma_f32_16x16x32_bf16 v[42:45], v[166:169], v[198:201], v[42:45]
	v_mfma_f32_16x16x32_bf16 v[30:33], v[158:161], v[206:209], v[30:33]
	v_mfma_f32_16x16x32_bf16 v[26:29], v[166:169], v[206:209], v[26:29]
	v_mfma_f32_16x16x32_bf16 v[14:17], v[158:161], v[214:217], v[14:17]
	v_mfma_f32_16x16x32_bf16 v[10:13], v[166:169], v[214:217], v[10:13]
	s_setprio 2
	s_setprio 0
	v_mfma_f32_16x16x32_bf16 v[54:57], v[170:173], v[186:189], 0
	v_mfma_f32_16x16x32_bf16 v[50:53], v[178:181], v[186:189], 0
	v_mfma_f32_16x16x32_bf16 v[38:41], v[170:173], v[194:197], 0
	v_mfma_f32_16x16x32_bf16 v[34:37], v[178:181], v[194:197], 0
	v_mfma_f32_16x16x32_bf16 v[22:25], v[170:173], v[202:205], 0
	v_mfma_f32_16x16x32_bf16 v[18:21], v[178:181], v[202:205], 0
	v_mfma_f32_16x16x32_bf16 v[6:9], v[170:173], v[210:213], 0
	v_mfma_f32_16x16x32_bf16 v[2:5], v[178:181], v[210:213], 0
	v_mfma_f32_16x16x32_bf16 v[54:57], v[174:177], v[190:193], v[54:57]
	v_mfma_f32_16x16x32_bf16 v[50:53], v[182:185], v[190:193], v[50:53]
	v_mfma_f32_16x16x32_bf16 v[38:41], v[174:177], v[198:201], v[38:41]
	v_mfma_f32_16x16x32_bf16 v[34:37], v[182:185], v[198:201], v[34:37]
	v_mfma_f32_16x16x32_bf16 v[22:25], v[174:177], v[206:209], v[22:25]
	v_mfma_f32_16x16x32_bf16 v[18:21], v[182:185], v[206:209], v[18:21]
	v_mfma_f32_16x16x32_bf16 v[6:9], v[174:177], v[214:217], v[6:9]
	v_mfma_f32_16x16x32_bf16 v[2:5], v[182:185], v[214:217], v[2:5]
	s_setprio 2
	s_barrier
; #define PG8_STAGE(bufoff, gbase, voff) do { _Pragma("unroll") for (int _i = 0; _i < 2; ++_i) \
;         __builtin_amdgcn_global_load_lds((const unsigned*)((const char*)(gbase) + (voff)[_i]), (LAS unsigned*)(lds + (bufoff) + ldsw + _i * 8192), 16, 0, 0); } while (0)
; #define PG8_LDA(dst, b, h) do { _Pragma("unroll") for (int m = 0; m < 4; ++m) _Pragma("unroll") for (int k = 0; k < 2; ++k) dst[m][k] = *(const LAS bf16x8*)(lds + PG8_SA(b, h) + aoff + m * 2048 + k * 1024); } while (0)
; #define PG8_LDB(dst, b, h) do { _Pragma("unroll") for (int n = 0; n < 2; ++n) _Pragma("unroll") for (int k = 0; k < 2; ++k) dst[n][k] = *(const LAS bf16x8*)(lds + PG8_SB(b, h) + boff + n * 2048 + k * 1024); } while (0)
; #define PG8_MMA(ai, bj, At, Bt) do { __builtin_amdgcn_s_setprio(1); _Pragma("unroll") for (int m = 0; m < 4; ++m) _Pragma("unroll") for (int n = 0; n < 2; ++n) _Pragma("unroll") for (int k = 0; k < 2; ++k) \
;         acc[ai][bj][m][n] = __builtin_amdgcn_mfma_f32_16x16x32_bf16(Bt[n][k], At[m][k], acc[ai][bj][m][n], 0, 0, 0); __builtin_amdgcn_s_setprio(0); } while (0)
; #define PG8_WAIT_V(n) asm volatile("s_waitcnt vmcnt(" #n ")" ::: "memory")
; #define PG8_WAIT_L(n) asm volatile("s_waitcnt lgkmcnt(" #n ")" ::: "memory")
; #define PG8_BAR __builtin_amdgcn_s_barrier()
; #define PG8_SCHED __builtin_amdgcn_sched_barrier(0)
; template <class Epi>
; __device__ __forceinline__ void gemm_phase(LAS unsigned char* lds, const Gemm g, int G, int c, const Epi& E) {
;     ...
;             PG8_LDB(B0, 1, 0); PG8_LDB(B1, 1, 1); PG8_SCHED; PG8_LDA(At, 1, 0); PG8_STAGE(PG8_SA(0, 1), a2 + hstepA, voffA);
;             PG8_WAIT_V(8); PG8_WAIT_L(0); PG8_BAR; PG8_MMA(0, 0, At, B0); PG8_MMA(0, 1, At, B1); PG8_BAR; PG8_SCHED;
	s_add_i32 s33, 0, 0x18000
	v_add_u32_e32 v157, s33, v151
	s_add_i32 s62, 0, 0x1c000
	ds_read_b128 v[146:149], v157
	ds_read_b128 v[158:161], v157 offset:1024
	ds_read_b128 v[162:165], v157 offset:2048
	ds_read_b128 v[166:169], v157 offset:3072
	v_add_u32_e32 v157, s62, v151
	ds_read_b128 v[170:173], v157
	ds_read_b128 v[174:177], v157 offset:1024
	ds_read_b128 v[178:181], v157 offset:2048
	ds_read_b128 v[182:185], v157 offset:3072
	s_add_u32 s48, s48, 0x40000
	s_addc_u32 s49, s49, 0
	s_mov_b32 m0, s58
	v_lshl_add_u64 v[226:227], s[48:49], 0, v[130:131]
	ds_read_b128 v[186:189], v154 offset:32768
	ds_read_b128 v[190:193], v154 offset:33792
	ds_read_b128 v[194:197], v154 offset:34816
	ds_read_b128 v[198:201], v154 offset:35840
	ds_read_b128 v[202:205], v154 offset:36864
	ds_read_b128 v[206:209], v154 offset:37888
	ds_read_b128 v[210:213], v154 offset:38912
	ds_read_b128 v[214:217], v154 offset:39936
	global_load_lds_dwordx4 v[226:227], off
	v_lshl_add_u64 v[226:227], s[48:49], 0, v[134:135]
	s_mov_b32 m0, s59
	s_nop 0
	global_load_lds_dwordx4 v[226:227], off
	s_waitcnt vmcnt(8)
	s_waitcnt lgkmcnt(0)
	s_barrier
	s_setprio 0
	v_mfma_f32_16x16x32_bf16 v[126:129], v[146:149], v[186:189], v[126:129]
	v_mfma_f32_16x16x32_bf16 v[122:125], v[162:165], v[186:189], v[122:125]
	v_mfma_f32_16x16x32_bf16 v[110:113], v[146:149], v[194:197], v[110:113]
	v_mfma_f32_16x16x32_bf16 v[106:109], v[162:165], v[194:197], v[106:109]
	v_mfma_f32_16x16x32_bf16 v[94:97], v[146:149], v[202:205], v[94:97]
	v_mfma_f32_16x16x32_bf16 v[90:93], v[162:165], v[202:205], v[90:93]
	v_mfma_f32_16x16x32_bf16 v[78:81], v[146:149], v[210:213], v[78:81]
	v_mfma_f32_16x16x32_bf16 v[74:77], v[162:165], v[210:213], v[74:77]
	v_mfma_f32_16x16x32_bf16 v[126:129], v[158:161], v[190:193], v[126:129]
	v_mfma_f32_16x16x32_bf16 v[122:125], v[166:169], v[190:193], v[122:125]
	v_mfma_f32_16x16x32_bf16 v[110:113], v[158:161], v[198:201], v[110:113]
	v_mfma_f32_16x16x32_bf16 v[106:109], v[166:169], v[198:201], v[106:109]
	v_mfma_f32_16x16x32_bf16 v[94:97], v[158:161], v[206:209], v[94:97]
	v_mfma_f32_16x16x32_bf16 v[90:93], v[166:169], v[206:209], v[90:93]
	v_mfma_f32_16x16x32_bf16 v[78:81], v[158:161], v[214:217], v[78:81]
	v_mfma_f32_16x16x32_bf16 v[74:77], v[166:169], v[214:217], v[74:77]
	s_setprio 2
	s_setprio 0
	v_mfma_f32_16x16x32_bf16 v[118:121], v[170:173], v[186:189], v[118:121]
	v_mfma_f32_16x16x32_bf16 v[114:117], v[178:181], v[186:189], v[114:117]
	v_mfma_f32_16x16x32_bf16 v[102:105], v[170:173], v[194:197], v[102:105]
	v_mfma_f32_16x16x32_bf16 v[98:101], v[178:181], v[194:197], v[98:101]
	v_mfma_f32_16x16x32_bf16 v[86:89], v[170:173], v[202:205], v[86:89]
	v_mfma_f32_16x16x32_bf16 v[82:85], v[178:181], v[202:205], v[82:85]
	v_mfma_f32_16x16x32_bf16 v[70:73], v[170:173], v[210:213], v[70:73]
	v_mfma_f32_16x16x32_bf16 v[66:69], v[178:181], v[210:213], v[66:69]
	v_mfma_f32_16x16x32_bf16 v[118:121], v[174:177], v[190:193], v[118:121]
	v_mfma_f32_16x16x32_bf16 v[114:117], v[182:185], v[190:193], v[114:117]
	v_mfma_f32_16x16x32_bf16 v[102:105], v[174:177], v[198:201], v[102:105]
	v_mfma_f32_16x16x32_bf16 v[98:101], v[182:185], v[198:201], v[98:101]
	v_mfma_f32_16x16x32_bf16 v[86:89], v[174:177], v[206:209], v[86:89]
	v_mfma_f32_16x16x32_bf16 v[82:85], v[182:185], v[206:209], v[82:85]
	v_mfma_f32_16x16x32_bf16 v[70:73], v[174:177], v[214:217], v[70:73]
	v_mfma_f32_16x16x32_bf16 v[66:69], v[182:185], v[214:217], v[66:69]
	s_setprio 2
	s_barrier
; #define PG8_STAGE(bufoff, gbase, voff) do { _Pragma("unroll") for (int _i = 0; _i < 2; ++_i) \
;         __builtin_amdgcn_global_load_lds((const unsigned*)((const char*)(gbase) + (voff)[_i]), (LAS unsigned*)(lds + (bufoff) + ldsw + _i * 8192), 16, 0, 0); } while (0)
; #define PG8_LDA(dst, b, h) do { _Pragma("unroll") for (int m = 0; m < 4; ++m) _Pragma("unroll") for (int k = 0; k < 2; ++k) dst[m][k] = *(const LAS bf16x8*)(lds + PG8_SA(b, h) + aoff + m * 2048 + k * 1024); } while (0)
; #define PG8_MMA(ai, bj, At, Bt) do { __builtin_amdgcn_s_setprio(1); _Pragma("unroll") for (int m = 0; m < 4; ++m) _Pragma("unroll") for (int n = 0; n < 2; ++n) _Pragma("unroll") for (int k = 0; k < 2; ++k) \
;         acc[ai][bj][m][n] = __builtin_amdgcn_mfma_f32_16x16x32_bf16(Bt[n][k], At[m][k], acc[ai][bj][m][n], 0, 0, 0); __builtin_amdgcn_s_setprio(0); } while (0)
; #define PG8_WAIT_V(n) asm volatile("s_waitcnt vmcnt(" #n ")" ::: "memory")
; #define PG8_WAIT_L(n) asm volatile("s_waitcnt lgkmcnt(" #n ")" ::: "memory")
; #define PG8_BAR __builtin_amdgcn_s_barrier()
; #define PG8_SCHED __builtin_amdgcn_sched_barrier(0)
; template <class Epi>
; __device__ __forceinline__ void gemm_phase(LAS unsigned char* lds, const Gemm g, int G, int c, const Epi& E) {
;     ...
;             PG8_LDA(At, 1, 1); PG8_STAGE(PG8_SB(1, 0), b3, voffB); PG8_STAGE(PG8_SB(1, 1), b3 + hstepB, voffB); PG8_STAGE(PG8_SA(1, 0), a3, voffA);
;             PG8_WAIT_V(8); PG8_WAIT_L(0); PG8_BAR; PG8_MMA(1, 0, At, B0); PG8_MMA(1, 1, At, B1); PG8_BAR; PG8_SCHED;
;         }
	s_add_i32 s33, s33, s56
	v_lshl_add_u64 v[218:219], v[218:219], 0, s[20:21]
	s_mov_b32 m0, s33
	ds_read_b128 v[186:189], v154 offset:49152
	ds_read_b128 v[190:193], v154 offset:50176
	ds_read_b128 v[194:197], v154 offset:51200
	ds_read_b128 v[198:201], v154 offset:52224
	ds_read_b128 v[202:205], v154 offset:53248
	ds_read_b128 v[206:209], v154 offset:54272
	ds_read_b128 v[210:213], v154 offset:55296
	ds_read_b128 v[214:217], v154 offset:56320
	global_load_lds_dwordx4 v[218:219], off
	s_add_i32 m0, s33, 0x2000
	s_add_u32 s46, s46, 0x40080
	v_lshl_add_u64 v[218:219], v[220:221], 0, s[20:21]
	s_addc_u32 s47, s47, 0
	s_add_i32 s33, s62, s56
	global_load_lds_dwordx4 v[218:219], off
	v_lshl_add_u64 v[218:219], s[46:47], 0, v[132:133]
	s_mov_b32 m0, s33
	s_nop 0
	global_load_lds_dwordx4 v[218:219], off
	v_lshl_add_u64 v[218:219], s[46:47], 0, v[136:137]
	s_add_i32 m0, s33, 0x2000
	s_nop 0
	global_load_lds_dwordx4 v[218:219], off
	v_lshl_add_u64 v[218:219], v[222:223], 0, s[20:21]
	s_mov_b32 m0, s67
	s_nop 0
	global_load_lds_dwordx4 v[218:219], off
	v_lshl_add_u64 v[218:219], v[224:225], 0, s[20:21]
	s_mov_b32 m0, s68
	s_nop 0
	global_load_lds_dwordx4 v[218:219], off
	s_waitcnt vmcnt(8)
	s_waitcnt lgkmcnt(0)
	s_barrier
	s_setprio 0
	v_mfma_f32_16x16x32_bf16 v[62:65], v[146:149], v[186:189], v[62:65]
	v_mfma_f32_16x16x32_bf16 v[58:61], v[162:165], v[186:189], v[58:61]
	v_mfma_f32_16x16x32_bf16 v[46:49], v[146:149], v[194:197], v[46:49]
	v_mfma_f32_16x16x32_bf16 v[42:45], v[162:165], v[194:197], v[42:45]
	v_mfma_f32_16x16x32_bf16 v[30:33], v[146:149], v[202:205], v[30:33]
	v_mfma_f32_16x16x32_bf16 v[26:29], v[162:165], v[202:205], v[26:29]
	v_mfma_f32_16x16x32_bf16 v[14:17], v[146:149], v[210:213], v[14:17]
	v_mfma_f32_16x16x32_bf16 v[10:13], v[162:165], v[210:213], v[10:13]
	v_mfma_f32_16x16x32_bf16 v[62:65], v[158:161], v[190:193], v[62:65]
	v_mfma_f32_16x16x32_bf16 v[58:61], v[166:169], v[190:193], v[58:61]
	v_mfma_f32_16x16x32_bf16 v[46:49], v[158:161], v[198:201], v[46:49]
	v_mfma_f32_16x16x32_bf16 v[42:45], v[166:169], v[198:201], v[42:45]
	v_mfma_f32_16x16x32_bf16 v[30:33], v[158:161], v[206:209], v[30:33]
	v_mfma_f32_16x16x32_bf16 v[26:29], v[166:169], v[206:209], v[26:29]
	v_mfma_f32_16x16x32_bf16 v[14:17], v[158:161], v[214:217], v[14:17]
	v_mfma_f32_16x16x32_bf16 v[10:13], v[166:169], v[214:217], v[10:13]
	s_setprio 2
	s_setprio 0
	v_mfma_f32_16x16x32_bf16 v[54:57], v[170:173], v[186:189], v[54:57]
	v_mfma_f32_16x16x32_bf16 v[50:53], v[178:181], v[186:189], v[50:53]
	v_mfma_f32_16x16x32_bf16 v[38:41], v[170:173], v[194:197], v[38:41]
	v_mfma_f32_16x16x32_bf16 v[34:37], v[178:181], v[194:197], v[34:37]
	v_mfma_f32_16x16x32_bf16 v[22:25], v[170:173], v[202:205], v[22:25]
	v_mfma_f32_16x16x32_bf16 v[18:21], v[178:181], v[202:205], v[18:21]
	v_mfma_f32_16x16x32_bf16 v[6:9], v[170:173], v[210:213], v[6:9]
	v_mfma_f32_16x16x32_bf16 v[2:5], v[178:181], v[210:213], v[2:5]
	v_mfma_f32_16x16x32_bf16 v[54:57], v[174:177], v[190:193], v[54:57]
	v_mfma_f32_16x16x32_bf16 v[50:53], v[182:185], v[190:193], v[50:53]
	v_mfma_f32_16x16x32_bf16 v[38:41], v[174:177], v[198:201], v[38:41]
	v_mfma_f32_16x16x32_bf16 v[34:37], v[182:185], v[198:201], v[34:37]
	v_mfma_f32_16x16x32_bf16 v[22:25], v[174:177], v[206:209], v[22:25]
	v_mfma_f32_16x16x32_bf16 v[18:21], v[182:185], v[206:209], v[18:21]
	v_mfma_f32_16x16x32_bf16 v[6:9], v[174:177], v[214:217], v[6:9]
	v_mfma_f32_16x16x32_bf16 v[2:5], v[182:185], v[214:217], v[2:5]
	s_setprio 2
	s_barrier
	s_add_i32 s81, s81, 2
	s_add_u32 s4, s4, 0x100
	s_addc_u32 s5, s5, 0
	s_add_u32 s41, s41, 0x100
	s_addc_u32 s80, s80, 0
	s_cmp_gt_u32 s81, 13
	s_cbranch_scc0 .LBB0_1297
